# write-through streaming cache policy (sc0 sc1 nt) on the ffn_up activation stores and both residual-GEMM x stores: less dirty L2 at the grid barriers / more L2 for GEMM operands
# speedup vs baseline: 1.0068x; 1.0068x over previous
; DI const float* modv(const P& p, int l, int mi) { return (const float*)(p.ws + OFF_MOD) + ((size_t)l * 9 + mi) * 6144; }
; static __device__ __forceinline__ void phase_resid_gemm(const P& p, int l, const u16* A, const u16* W, int ldk, int gate_off, char* lds, bool from_input = false) {
;     ...
;     float* xb = xrow(p, mt * 256); const float* gv = modv(p, l, modidx(mt * 256)) + gate_off;
; #pragma unroll
;     for (int tn = 0; tn < 2; ++tn) {
;       const int n = nt * 128 + wn * 64 + 32 * tn + r32; const float g = gv[n];
;       float* xp = xb + (size_t)(wm * 64 + 4 * hi) * DM + n;
;       const float* xs = (from_input ? xin(p, mt * 256) : (const float*)xb) + (size_t)(wm * 64 + 4 * hi) * DM + n;
;       float xv[2][16];
; #pragma unroll
;       for (int tm = 0; tm < 2; ++tm)
; #pragma unroll
;         for (int r = 0; r < 16; ++r) xv[tm][r] = __builtin_nontemporal_load(xs + (size_t)(32 * tm + (r & 3) + 8 * (r >> 2)) * DM);
.LBB0_910:
	s_lshl_b32 s22, s19, 8
	s_add_i32 s8, s22, 0xffff0000
	s_ashr_i32 s9, s22, 31
	s_cmpk_lt_i32 s19, 0x100
	v_readlane_b32 s36, v252, 21
	s_cselect_b32 s9, s9, 0
	s_cselect_b32 s8, s22, s8
	v_readlane_b32 s37, v252, 22
	v_readlane_b32 s40, v252, 25
	v_readlane_b32 s41, v252, 26
	s_cselect_b32 s19, s63, s65
	s_cselect_b32 s20, s62, s64
	s_cselect_b32 s23, s36, s40
	s_cselect_b32 s24, s37, s41
	s_lshl_b64 s[10:11], s[8:9], 12
	s_add_u32 s20, s20, s10
	s_addc_u32 s21, s19, s11
	s_min_i32 s8, s22, 0x10000
	s_ashr_i32 s8, s8, 13
	s_ashr_i32 s9, s8, 31
	s_add_u32 s8, s78, s8
	s_addc_u32 s9, s79, s9
	s_mulk_i32 s9, 0x6000
	s_mul_hi_u32 s19, s8, 0x6000
	s_add_i32 s19, s19, s9
	s_mulk_i32 s8, 0x6000
	s_add_u32 s8, s64, s8
	s_addc_u32 s9, s65, s19
	s_add_u32 s8, s8, 0x802000
	s_addc_u32 s9, s9, 0
	v_lshl_or_b32 v132, s16, 7, v211
	s_add_u32 s16, s23, s10
	s_addc_u32 s19, s24, s11
	v_readlane_b32 s10, v254, 58
	v_ashrrev_i32_e32 v133, 31, v132
	v_readlane_b32 s11, v254, 59
	v_lshlrev_b64 v[202:203], 2, v[132:133]
	s_and_b64 s[10:11], s[10:11], exec
	v_lshl_add_u64 v[134:135], s[8:9], 0, v[202:203]
	s_cselect_b32 s11, s19, s21
	s_cselect_b32 s10, s16, s20
	global_load_dword v0, v[134:135], off
	v_lshl_add_u64 v[134:135], s[10:11], 0, v[130:131]
	v_lshl_add_u64 v[134:135], v[134:135], 0, v[202:203]
	s_movk_i32 s14, 0x1000
	v_add_co_u32_e32 v136, vcc, s14, v134
	s_movk_i32 s15, 0x2000
	s_nop 0
	v_addc_co_u32_e32 v137, vcc, 0, v135, vcc
	v_add_co_u32_e32 v138, vcc, s15, v134
	s_movk_i32 s16, 0x3000
	s_nop 0
	v_addc_co_u32_e32 v139, vcc, 0, v135, vcc
	v_add_co_u32_e32 v140, vcc, s16, v134
	s_mov_b32 s11, 0x9000
	s_nop 0
	v_addc_co_u32_e32 v141, vcc, 0, v135, vcc
	v_add_co_u32_e32 v142, vcc, s11, v134
	v_lshl_add_u64 v[194:195], s[20:21], 0, v[130:131]
	s_nop 0
	v_addc_co_u32_e32 v143, vcc, 0, v135, vcc
	s_mov_b32 s20, 0xb000
	v_add_co_u32_e32 v144, vcc, s20, v134
	s_mov_b32 s10, 0x8000
	s_nop 0
	v_addc_co_u32_e32 v145, vcc, 0, v135, vcc
	v_add_co_u32_e32 v148, vcc, s10, v134
	s_mov_b32 s19, 0xa000
	s_nop 0
	v_addc_co_u32_e32 v149, vcc, 0, v135, vcc
	v_readlane_b32 s39, v252, 24
	v_add_co_u32_e32 v152, vcc, s19, v134
	s_mov_b32 s39, 0x10000
	s_nop 0
	v_addc_co_u32_e32 v153, vcc, 0, v135, vcc
	v_add_co_u32_e32 v146, vcc, s39, v134
	s_mov_b32 s21, 0x11000
	s_nop 0
	v_addc_co_u32_e32 v147, vcc, 0, v135, vcc
	v_add_co_u32_e32 v150, vcc, s21, v134
	s_mov_b32 s22, 0x12000
	s_nop 0
	v_addc_co_u32_e32 v151, vcc, 0, v135, vcc
	v_add_co_u32_e32 v154, vcc, s22, v134
	s_mov_b32 s23, 0x13000
	s_nop 0
	v_addc_co_u32_e32 v155, vcc, 0, v135, vcc
	v_add_co_u32_e32 v156, vcc, s23, v134
	s_mov_b32 s24, 0x18000
	s_nop 0
	v_addc_co_u32_e32 v157, vcc, 0, v135, vcc
	v_add_co_u32_e32 v158, vcc, s24, v134
	s_mov_b32 s25, 0x19000
	s_nop 0
	v_addc_co_u32_e32 v159, vcc, 0, v135, vcc
	v_add_co_u32_e32 v160, vcc, s25, v134
	s_mov_b32 s27, 0x1a000
	s_nop 0
	v_addc_co_u32_e32 v161, vcc, 0, v135, vcc
	v_add_co_u32_e32 v162, vcc, s27, v134
	s_mov_b32 s28, 0x1b000
	s_nop 0
	v_addc_co_u32_e32 v163, vcc, 0, v135, vcc
	v_add_co_u32_e32 v164, vcc, s28, v134
	global_load_dword v133, v[134:135], off nt
	global_load_dword v204, v[138:139], off offset:-4096 nt
	global_load_dword v205, v[138:139], off nt
	global_load_dword v208, v[142:143], off offset:-4096 nt
	global_load_dword v209, v[142:143], off nt
	global_load_dword v215, v[144:145], off offset:-4096 nt
	global_load_dword v216, v[144:145], off nt
	global_load_dword v206, v[140:141], off nt
	v_addc_co_u32_e32 v165, vcc, 0, v135, vcc
	s_mov_b32 s29, 0x20000
	v_add_co_u32_e32 v166, vcc, s29, v134
	s_mov_b32 s30, 0x21000
	s_nop 0
	v_addc_co_u32_e32 v167, vcc, 0, v135, vcc
	v_add_co_u32_e32 v168, vcc, s30, v134
	s_mov_b32 s31, 0x22000
	s_nop 0
	v_addc_co_u32_e32 v169, vcc, 0, v135, vcc
	v_add_co_u32_e32 v170, vcc, s31, v134
	s_mov_b32 s33, 0x23000
	s_nop 0
	v_addc_co_u32_e32 v171, vcc, 0, v135, vcc
	v_add_co_u32_e32 v172, vcc, s33, v134
	s_mov_b32 s34, 0x28000
	s_nop 0
	v_addc_co_u32_e32 v173, vcc, 0, v135, vcc
	v_add_co_u32_e32 v174, vcc, s34, v134
	s_mov_b32 s35, 0x29000
	s_nop 0
	v_addc_co_u32_e32 v175, vcc, 0, v135, vcc
	v_add_co_u32_e32 v176, vcc, s35, v134
	s_mov_b32 s36, 0x2a000
	s_nop 0
	v_addc_co_u32_e32 v177, vcc, 0, v135, vcc
	v_add_co_u32_e32 v178, vcc, s36, v134
	s_mov_b32 s37, 0x2b000
	s_nop 0
	v_addc_co_u32_e32 v179, vcc, 0, v135, vcc
	v_readlane_b32 s38, v252, 23
	v_add_co_u32_e32 v180, vcc, s37, v134
	s_mov_b32 s38, 0x30000
	s_nop 0
	v_addc_co_u32_e32 v181, vcc, 0, v135, vcc
	v_add_co_u32_e32 v182, vcc, s38, v134
	global_load_dword v217, v[150:151], off offset:-4096 nt
	global_load_dword v218, v[150:151], off nt
	global_load_dword v219, v[156:157], off offset:-4096 nt
	global_load_dword v220, v[156:157], off nt
	global_load_dword v221, v[160:161], off offset:-4096 nt
	global_load_dword v222, v[160:161], off nt
	global_load_dword v223, v[164:165], off offset:-4096 nt
	global_load_dword v238, v[164:165], off nt
	v_addc_co_u32_e32 v183, vcc, 0, v135, vcc
	s_mov_b32 s40, 0x31000
	v_add_co_u32_e32 v184, vcc, s40, v134
	s_mov_b32 s41, 0x32000
	s_nop 0
	v_addc_co_u32_e32 v185, vcc, 0, v135, vcc
	v_readlane_b32 s42, v252, 27
	v_add_co_u32_e32 v186, vcc, s41, v134
	s_mov_b32 s42, 0x33000
	s_nop 0
	v_addc_co_u32_e32 v187, vcc, 0, v135, vcc
	v_readlane_b32 s43, v252, 28
	v_add_co_u32_e32 v188, vcc, s42, v134
	s_mov_b32 s43, 0x38000
	s_nop 0
	v_addc_co_u32_e32 v189, vcc, 0, v135, vcc
	v_readlane_b32 s44, v252, 29
	v_add_co_u32_e32 v190, vcc, s43, v134
	global_load_dword v239, v[168:169], off offset:-4096 nt
	global_load_dword v240, v[168:169], off nt
	global_load_dword v241, v[172:173], off offset:-4096 nt
	global_load_dword v242, v[172:173], off nt
	global_load_dword v243, v[176:177], off offset:-4096 nt
	global_load_dword v244, v[176:177], off nt
	global_load_dword v245, v[180:181], off offset:-4096 nt
	global_load_dword v246, v[180:181], off nt
	v_addc_co_u32_e32 v191, vcc, 0, v135, vcc
	s_mov_b32 s44, 0x39000
	v_readlane_b32 s45, v252, 30
	v_add_co_u32_e32 v192, vcc, s44, v134
	s_mov_b32 s45, 0x3a000
	s_nop 0
	v_addc_co_u32_e32 v193, vcc, 0, v135, vcc
	v_readlane_b32 s46, v252, 31
	v_add_co_u32_e32 v196, vcc, s45, v134
	s_mov_b32 s46, 0x3b000
	s_nop 0
	v_addc_co_u32_e32 v197, vcc, 0, v135, vcc
	v_add_co_u32_e32 v200, vcc, s46, v134
	v_lshl_add_u64 v[194:195], v[194:195], 0, v[202:203]
	s_nop 0
	v_addc_co_u32_e32 v201, vcc, 0, v135, vcc
	global_load_dword v247, v[184:185], off offset:-4096 nt
	global_load_dword v248, v[184:185], off nt
	global_load_dword v249, v[188:189], off offset:-4096 nt
	global_load_dword v250, v[188:189], off nt
	global_load_dword v251, v[192:193], off offset:-4096 nt
	global_load_dword v226, v[192:193], off nt
	global_load_dword v229, v[200:201], off offset:-4096 nt
	global_load_dword v231, v[200:201], off nt
	s_waitcnt vmcnt(31)
; static __device__ __forceinline__ void phase_resid_gemm(const P& p, int l, const u16* A, const u16* W, int ldk, int gate_off, char* lds, bool from_input = false) {
;     ...
;       float xv[2][16];
; #pragma unroll
;       for (int tm = 0; tm < 2; ++tm)
; #pragma unroll
;         for (int r = 0; r < 16; ++r) xv[tm][r] = __builtin_nontemporal_load(xs + (size_t)(32 * tm + (r & 3) + 8 * (r >> 2)) * DM);
; #pragma unroll
;       for (int tm = 0; tm < 2; ++tm)
; #pragma unroll
;         for (int r = 0; r < 16; ++r) xp[(size_t)(32 * tm + (r & 3) + 8 * (r >> 2)) * DM] = xv[tm][r] + g * acc[tm][tn][r];
	v_fmac_f32_e32 v133, v50, v0
	v_add_co_u32_e32 v50, vcc, s14, v194
	s_waitcnt vmcnt(30)
	v_fmac_f32_e32 v204, v51, v0
	v_addc_co_u32_e32 v51, vcc, 0, v195, vcc
	v_add_co_u32_e32 v202, vcc, s15, v194
	s_waitcnt vmcnt(29)
	v_fmac_f32_e32 v205, v52, v0
	v_addc_co_u32_e32 v203, vcc, 0, v195, vcc
	v_add_co_u32_e32 v52, vcc, s16, v194
	s_waitcnt vmcnt(24)
	v_fmac_f32_e32 v206, v53, v0
	v_addc_co_u32_e32 v53, vcc, 0, v195, vcc
	global_store_dword v[202:203], v204, off offset:-4096 sc0 sc1 nt
	v_add_co_u32_e32 v204, vcc, s10, v194
	global_store_dword v[202:203], v205, off sc0 sc1 nt
	s_nop 0
	v_addc_co_u32_e32 v205, vcc, 0, v195, vcc
	global_store_dword v[52:53], v206, off sc0 sc1 nt
	v_add_co_u32_e32 v206, vcc, s11, v194
	v_fmac_f32_e32 v208, v54, v0
	s_nop 0
	v_addc_co_u32_e32 v207, vcc, 0, v195, vcc
	v_add_co_u32_e32 v54, vcc, s19, v194
	v_fmac_f32_e32 v209, v55, v0
	s_nop 0
	v_addc_co_u32_e32 v55, vcc, 0, v195, vcc
	global_store_dword v[206:207], v208, off offset:-4096 sc0 sc1 nt
	v_add_co_u32_e32 v208, vcc, s20, v194
	global_store_dword v[206:207], v209, off sc0 sc1 nt
	s_nop 0
	v_addc_co_u32_e32 v209, vcc, 0, v195, vcc
	v_fmac_f32_e32 v215, v56, v0
	v_add_co_u32_e32 v56, vcc, s21, v194
	v_fmac_f32_e32 v216, v57, v0
	s_nop 0
	v_addc_co_u32_e32 v57, vcc, 0, v195, vcc
	s_waitcnt vmcnt(28)
	v_fmac_f32_e32 v217, v58, v0
	v_add_co_u32_e32 v58, vcc, s23, v194
	s_waitcnt vmcnt(27)
	v_fmac_f32_e32 v218, v59, v0
	v_addc_co_u32_e32 v59, vcc, 0, v195, vcc
	s_waitcnt vmcnt(26)
	v_fmac_f32_e32 v219, v60, v0
	v_add_co_u32_e32 v60, vcc, s25, v194
	s_waitcnt vmcnt(25)
	v_fmac_f32_e32 v220, v61, v0
	v_addc_co_u32_e32 v61, vcc, 0, v195, vcc
	s_waitcnt vmcnt(24)
	v_fmac_f32_e32 v221, v62, v0
	v_add_co_u32_e32 v62, vcc, s28, v194
	s_waitcnt vmcnt(23)
	v_fmac_f32_e32 v222, v63, v0
	v_addc_co_u32_e32 v63, vcc, 0, v195, vcc
	s_waitcnt vmcnt(22)
	v_fmac_f32_e32 v223, v64, v0
	v_add_co_u32_e32 v64, vcc, s30, v194
	s_waitcnt vmcnt(21)
	v_fmac_f32_e32 v238, v65, v0
	v_addc_co_u32_e32 v65, vcc, 0, v195, vcc
	s_waitcnt vmcnt(20)
	v_fmac_f32_e32 v239, v34, v0
	v_add_co_u32_e32 v34, vcc, s33, v194
	s_waitcnt vmcnt(19)
	v_fmac_f32_e32 v240, v35, v0
	v_addc_co_u32_e32 v35, vcc, 0, v195, vcc
	s_waitcnt vmcnt(18)
	v_fmac_f32_e32 v241, v36, v0
	v_add_co_u32_e32 v36, vcc, s35, v194
	s_waitcnt vmcnt(17)
	v_fmac_f32_e32 v242, v37, v0
	v_addc_co_u32_e32 v37, vcc, 0, v195, vcc
	s_waitcnt vmcnt(16)
	v_fmac_f32_e32 v243, v38, v0
	v_add_co_u32_e32 v38, vcc, s37, v194
	s_waitcnt vmcnt(15)
	v_fmac_f32_e32 v244, v39, v0
	v_addc_co_u32_e32 v39, vcc, 0, v195, vcc
	s_waitcnt vmcnt(14)
	v_fmac_f32_e32 v245, v40, v0
	v_add_co_u32_e32 v40, vcc, s40, v194
	s_waitcnt vmcnt(13)
	v_fmac_f32_e32 v246, v41, v0
	v_addc_co_u32_e32 v41, vcc, 0, v195, vcc
	s_waitcnt vmcnt(12)
	v_fmac_f32_e32 v247, v42, v0
	v_add_co_u32_e32 v42, vcc, s42, v194
	s_waitcnt vmcnt(11)
	v_fmac_f32_e32 v248, v43, v0
	v_addc_co_u32_e32 v43, vcc, 0, v195, vcc
	s_waitcnt vmcnt(10)
	v_fmac_f32_e32 v249, v44, v0
	v_add_co_u32_e32 v44, vcc, s44, v194
	s_waitcnt vmcnt(9)
	v_fmac_f32_e32 v250, v45, v0
	v_addc_co_u32_e32 v45, vcc, 0, v195, vcc
	s_waitcnt vmcnt(8)
	v_fmac_f32_e32 v251, v46, v0
	s_waitcnt vmcnt(6)
	v_fmac_f32_e32 v229, v48, v0
	v_add_co_u32_e32 v46, vcc, s46, v194
	v_or_b32_e32 v48, 32, v132
	v_fmac_f32_e32 v226, v47, v0
	v_addc_co_u32_e32 v47, vcc, 0, v195, vcc
	s_waitcnt vmcnt(5)
	v_fmac_f32_e32 v231, v49, v0
	v_ashrrev_i32_e32 v49, 31, v48
	global_store_dword v[194:195], v133, off sc0 sc1 nt
	global_store_dword v[208:209], v215, off offset:-4096 sc0 sc1 nt
	global_store_dword v[208:209], v216, off sc0 sc1 nt
	global_store_dword v[56:57], v217, off offset:-4096 sc0 sc1 nt
	global_store_dword v[56:57], v218, off sc0 sc1 nt
	global_store_dword v[58:59], v219, off offset:-4096 sc0 sc1 nt
	global_store_dword v[58:59], v220, off sc0 sc1 nt
	global_store_dword v[60:61], v221, off offset:-4096 sc0 sc1 nt
	global_store_dword v[60:61], v222, off sc0 sc1 nt
	global_store_dword v[62:63], v223, off offset:-4096 sc0 sc1 nt
	global_store_dword v[62:63], v238, off sc0 sc1 nt
	global_store_dword v[64:65], v239, off offset:-4096 sc0 sc1 nt
	global_store_dword v[64:65], v240, off sc0 sc1 nt
	global_store_dword v[34:35], v241, off offset:-4096 sc0 sc1 nt
	global_store_dword v[34:35], v242, off sc0 sc1 nt
	global_store_dword v[36:37], v243, off offset:-4096 sc0 sc1 nt
	global_store_dword v[36:37], v244, off sc0 sc1 nt
	global_store_dword v[38:39], v245, off offset:-4096 sc0 sc1 nt
	global_store_dword v[38:39], v246, off sc0 sc1 nt
	global_store_dword v[40:41], v247, off offset:-4096 sc0 sc1 nt
	global_store_dword v[40:41], v248, off sc0 sc1 nt
	global_store_dword v[42:43], v249, off offset:-4096 sc0 sc1 nt
	global_store_dword v[42:43], v250, off sc0 sc1 nt
	global_store_dword v[44:45], v251, off offset:-4096 sc0 sc1 nt
	global_store_dword v[44:45], v226, off sc0 sc1 nt
	global_store_dword v[46:47], v229, off offset:-4096 sc0 sc1 nt
	global_store_dword v[46:47], v231, off sc0 sc1 nt
	v_lshl_add_u64 v[48:49], v[48:49], 2, s[8:9]
	global_load_dword v0, v[48:49], off
	global_load_dword v215, v[134:135], off offset:128 nt
	global_load_dword v216, v[138:139], off offset:128 nt
	global_load_dword v217, v[136:137], off offset:128 nt
	global_load_dword v218, v[140:141], off offset:128 nt
	global_load_dword v219, v[148:149], off offset:128 nt
	global_load_dword v220, v[152:153], off offset:128 nt
	global_load_dword v221, v[142:143], off offset:128 nt
	global_load_dword v222, v[144:145], off offset:128 nt
	global_load_dword v223, v[146:147], off offset:128 nt
	s_nop 0
	global_load_dword v154, v[154:155], off offset:128 nt
	s_nop 0
; static __device__ __forceinline__ void phase_resid_gemm(const P& p, int l, const u16* A, const u16* W, int ldk, int gate_off, char* lds, bool from_input = false) {
;     ...
;       float xv[2][16];
; #pragma unroll
;       for (int tm = 0; tm < 2; ++tm)
; #pragma unroll
;         for (int r = 0; r < 16; ++r) xv[tm][r] = __builtin_nontemporal_load(xs + (size_t)(32 * tm + (r & 3) + 8 * (r >> 2)) * DM);
; #pragma unroll
;       for (int tm = 0; tm < 2; ++tm)
; #pragma unroll
;         for (int r = 0; r < 16; ++r) xp[(size_t)(32 * tm + (r & 3) + 8 * (r >> 2)) * DM] = xv[tm][r] + g * acc[tm][tn][r];
	global_load_dword v155, v[150:151], off offset:128 nt
	s_nop 0
	global_load_dword v156, v[156:157], off offset:128 nt
	s_nop 0
	global_load_dword v157, v[158:159], off offset:128 nt
	s_nop 0
	global_load_dword v158, v[162:163], off offset:128 nt
	global_load_dword v159, v[160:161], off offset:128 nt
	s_nop 0
	global_load_dword v160, v[164:165], off offset:128 nt
	global_load_dword v161, v[166:167], off offset:128 nt
	global_load_dword v162, v[168:169], off offset:128 nt
	global_load_dword v163, v[170:171], off offset:128 nt
	s_nop 0
	global_load_dword v164, v[172:173], off offset:128 nt
	global_load_dword v165, v[174:175], off offset:128 nt
	global_load_dword v166, v[178:179], off offset:128 nt
	global_load_dword v167, v[176:177], off offset:128 nt
	global_load_dword v168, v[180:181], off offset:128 nt
	global_load_dword v169, v[182:183], off offset:128 nt
	global_load_dword v170, v[186:187], off offset:128 nt
	global_load_dword v171, v[184:185], off offset:128 nt
	global_load_dword v172, v[188:189], off offset:128 nt
	global_load_dword v173, v[190:191], off offset:128 nt
	global_load_dword v174, v[196:197], off offset:128 nt
	global_load_dword v175, v[192:193], off offset:128 nt
	global_load_dword v176, v[200:201], off offset:128 nt
	v_add_co_u32_e32 v48, vcc, s39, v194
	s_movk_i32 s80, 0x1000
	s_nop 0
	v_addc_co_u32_e32 v49, vcc, 0, v195, vcc
	v_add_co_u32_e32 v132, vcc, s22, v194
	s_movk_i32 s81, 0x2000
	s_nop 0
	v_addc_co_u32_e32 v133, vcc, 0, v195, vcc
	v_add_co_u32_e32 v134, vcc, s24, v194
	s_mov_b32 s40, 0x800000
	s_nop 0
	v_addc_co_u32_e32 v135, vcc, 0, v195, vcc
	v_add_co_u32_e32 v136, vcc, s27, v194
	v_readlane_b32 s47, v252, 32
	s_nop 0
	v_addc_co_u32_e32 v137, vcc, 0, v195, vcc
	v_add_co_u32_e32 v138, vcc, s29, v194
	v_readlane_b32 s48, v252, 33
	s_nop 0
	v_addc_co_u32_e32 v139, vcc, 0, v195, vcc
	v_add_co_u32_e32 v140, vcc, s31, v194
	v_readlane_b32 s49, v252, 34
	s_nop 0
	v_addc_co_u32_e32 v141, vcc, 0, v195, vcc
	v_add_co_u32_e32 v142, vcc, s34, v194
	v_readlane_b32 s50, v252, 35
	s_nop 0
	v_addc_co_u32_e32 v143, vcc, 0, v195, vcc
	v_add_co_u32_e32 v144, vcc, s36, v194
	v_readlane_b32 s51, v252, 36
	s_nop 0
	v_addc_co_u32_e32 v145, vcc, 0, v195, vcc
	v_add_co_u32_e32 v146, vcc, s38, v194
	s_waitcnt vmcnt(31)
	v_fmac_f32_e32 v215, v18, v0
	v_addc_co_u32_e32 v147, vcc, 0, v195, vcc
	v_add_co_u32_e32 v148, vcc, s41, v194
	s_waitcnt vmcnt(29)
	v_fmac_f32_e32 v217, v19, v0
	v_addc_co_u32_e32 v149, vcc, 0, v195, vcc
	v_add_co_u32_e32 v150, vcc, s43, v194
	v_readlane_b32 s42, v254, 60
	s_nop 0
	v_addc_co_u32_e32 v151, vcc, 0, v195, vcc
	v_add_co_u32_e32 v152, vcc, s45, v194
	v_fmac_f32_e32 v216, v20, v0
	s_nop 0
	v_addc_co_u32_e32 v153, vcc, 0, v195, vcc
	s_waitcnt vmcnt(28)
	v_fmac_f32_e32 v218, v21, v0
	s_waitcnt vmcnt(27)
	v_fmac_f32_e32 v219, v22, v0
	s_waitcnt vmcnt(25)
	v_fmac_f32_e32 v221, v23, v0
	v_fmac_f32_e32 v220, v24, v0
	s_waitcnt vmcnt(24)
	v_fmac_f32_e32 v222, v25, v0
	s_waitcnt vmcnt(23)
	v_fmac_f32_e32 v223, v26, v0
	s_waitcnt vmcnt(21)
	v_fmac_f32_e32 v155, v27, v0
	v_fmac_f32_e32 v154, v28, v0
	s_waitcnt vmcnt(20)
	v_fmac_f32_e32 v156, v29, v0
	s_waitcnt vmcnt(19)
	v_fmac_f32_e32 v157, v30, v0
	s_waitcnt vmcnt(17)
	v_fmac_f32_e32 v159, v31, v0
	v_fmac_f32_e32 v158, v32, v0
	s_waitcnt vmcnt(16)
	v_fmac_f32_e32 v160, v33, v0
	s_waitcnt vmcnt(15)
	v_fmac_f32_e32 v161, v2, v0
	s_waitcnt vmcnt(14)
	v_fmac_f32_e32 v162, v3, v0
	s_waitcnt vmcnt(13)
	v_fmac_f32_e32 v163, v4, v0
	s_waitcnt vmcnt(12)
	v_fmac_f32_e32 v164, v5, v0
	s_waitcnt vmcnt(11)
	v_fmac_f32_e32 v165, v6, v0
	s_waitcnt vmcnt(9)
	v_fmac_f32_e32 v167, v7, v0
	v_fmac_f32_e32 v166, v8, v0
	s_waitcnt vmcnt(8)
	v_fmac_f32_e32 v168, v9, v0
	s_waitcnt vmcnt(7)
	v_fmac_f32_e32 v169, v10, v0
	s_waitcnt vmcnt(5)
	v_fmac_f32_e32 v171, v11, v0
	v_fmac_f32_e32 v170, v12, v0
	s_waitcnt vmcnt(4)
	v_fmac_f32_e32 v172, v13, v0
	s_waitcnt vmcnt(3)
	v_fmac_f32_e32 v173, v14, v0
	s_waitcnt vmcnt(1)
	v_fmac_f32_e32 v175, v15, v0
	v_fmac_f32_e32 v174, v16, v0
	s_waitcnt vmcnt(0)
	v_fmac_f32_e32 v176, v17, v0
	s_andn2_b64 vcc, exec, s[6:7]
	s_movk_i32 s41, 0x420
	v_readlane_b32 s43, v254, 61
	global_store_dword v[194:195], v215, off offset:128 sc0 sc1 nt
	global_store_dword v[50:51], v217, off offset:128 sc0 sc1 nt
	global_store_dword v[202:203], v216, off offset:128 sc0 sc1 nt
	global_store_dword v[52:53], v218, off offset:128 sc0 sc1 nt
	global_store_dword v[204:205], v219, off offset:128 sc0 sc1 nt
	global_store_dword v[206:207], v221, off offset:128 sc0 sc1 nt
	global_store_dword v[54:55], v220, off offset:128 sc0 sc1 nt
	global_store_dword v[208:209], v222, off offset:128 sc0 sc1 nt
	global_store_dword v[48:49], v223, off offset:128 sc0 sc1 nt
	global_store_dword v[56:57], v155, off offset:128 sc0 sc1 nt
	global_store_dword v[132:133], v154, off offset:128 sc0 sc1 nt
	global_store_dword v[58:59], v156, off offset:128 sc0 sc1 nt
	global_store_dword v[134:135], v157, off offset:128 sc0 sc1 nt
	global_store_dword v[60:61], v159, off offset:128 sc0 sc1 nt
	global_store_dword v[136:137], v158, off offset:128 sc0 sc1 nt
	global_store_dword v[62:63], v160, off offset:128 sc0 sc1 nt
	global_store_dword v[138:139], v161, off offset:128 sc0 sc1 nt
	global_store_dword v[64:65], v162, off offset:128 sc0 sc1 nt
	global_store_dword v[140:141], v163, off offset:128 sc0 sc1 nt
	global_store_dword v[34:35], v164, off offset:128 sc0 sc1 nt
	global_store_dword v[142:143], v165, off offset:128 sc0 sc1 nt
	global_store_dword v[36:37], v167, off offset:128 sc0 sc1 nt
	global_store_dword v[144:145], v166, off offset:128 sc0 sc1 nt
	global_store_dword v[38:39], v168, off offset:128 sc0 sc1 nt
	global_store_dword v[146:147], v169, off offset:128 sc0 sc1 nt
	global_store_dword v[40:41], v171, off offset:128 sc0 sc1 nt
	global_store_dword v[148:149], v170, off offset:128 sc0 sc1 nt
	global_store_dword v[42:43], v172, off offset:128 sc0 sc1 nt
	global_store_dword v[150:151], v173, off offset:128 sc0 sc1 nt
	global_store_dword v[44:45], v175, off offset:128 sc0 sc1 nt
	global_store_dword v[152:153], v174, off offset:128 sc0 sc1 nt
	global_store_dword v[46:47], v176, off offset:128 sc0 sc1 nt
	s_cbranch_vccz .LBB0_929

; DI float silu_f(float g) { return g * rcpf_(1.f + ex2(-g * LOG2E)); }
; static __device__ __forceinline__ void phase_ffn_up(const P& p, int l, char* lds) {
;     ...
; #pragma unroll
;     for (int tm = 0; tm < 4; ++tm) {
;       char* trow = tile + (wm * 64 + 16 * tm + (lane & 15)) * 528 + (wn * 64 + 4 * (lane >> 4)) * 4;
; #pragma unroll
;       for (int tn = 0; tn < 4; ++tn) *(f32x4*)(trow + 64 * tn) = acc[tm][tn];
;     }
;     __syncthreads();
;     {
;       const int cgp = tid & 7, wn2 = cgp >> 2, j0 = (cgp & 3) * 8;
;       const int ca0 = nt * 64 + wn2 * 32 + j0;
;       const int lca = (wn2 * 64 + j0) * 4, lcg = lca + 128;
;       float wa0[8], wa1[8], wa2[8], ba[8], wg0[8], wg1[8], wg2[8], bg[8];
; #pragma unroll
;       for (int e = 0; e < 8; ++e) {
;         wa0[e] = cw[ca0 + e]; wa1[e] = cw[5632 + ca0 + e]; wa2[e] = cw[2 * 5632 + ca0 + e]; ba[e] = cb[ca0 + e];
;         wg0[e] = cw[DFF + ca0 + e]; wg1[e] = cw[5632 + DFF + ca0 + e]; wg2[e] = cw[2 * 5632 + DFF + ca0 + e]; bg[e] = cb[DFF + ca0 + e];
;       }
; #pragma unroll
;       for (int jj = 0; jj < 4; ++jj) {
;         const int r = (tid >> 3) + 64 * jj, tt = tstart + r;
;         if (r >= 1 && r <= 254 && tt < MEND) {
;           const int pos = tt < MLAT ? (tt & (TLAT - 1)) : ((tt - MLAT) & (TCTX - 1)), slen = tt < MLAT ? TLAT : TCTX;
;           const float fm = pos == 0 ? 0.f : 1.f, fp = pos == slen - 1 ? 0.f : 1.f;
;           const char* rp = tile + r * 528;
;           float o[8];
; #pragma unroll
;           for (int hf = 0; hf < 2; ++hf) {
;             const f32x4 am = *(const f32x4*)(rp - 528 + lca + hf * 16), a0 = *(const f32x4*)(rp + lca + hf * 16), ap = *(const f32x4*)(rp + 528 + lca + hf * 16);
;             const f32x4 gm = *(const f32x4*)(rp - 528 + lcg + hf * 16), g0 = *(const f32x4*)(rp + lcg + hf * 16), gp = *(const f32x4*)(rp + 528 + lcg + hf * 16);
; #pragma unroll
;             for (int e = 0; e < 4; ++e) {
;               const int q = hf * 4 + e;
;               const float ua = wa0[q] * (fm * am[e]) + wa1[q] * a0[e] + wa2[q] * (fp * ap[e]) + ba[q];
;               const float ug = wg0[q] * (fm * gm[e]) + wg1[q] * g0[e] + wg2[q] * (fp * gp[e]) + bg[q];
;               o[q] = silu_f(ug) * ua;
.LBB0_1077:
	v_lshl_or_b32 v114, s35, 6, v152
	v_ashrrev_i32_e32 v115, 31, v114
	ds_write_b128 v155, v[50:53] offset:2304
	ds_write_b128 v155, v[54:57] offset:2368
	ds_write_b128 v155, v[58:61] offset:2432
	ds_write_b128 v155, v[62:65] offset:2496
	ds_write_b128 v155, v[66:69] offset:10752
	ds_write_b128 v155, v[70:73] offset:10816
	ds_write_b128 v155, v[74:77] offset:10880
	ds_write_b128 v155, v[78:81] offset:10944
	ds_write_b128 v155, v[82:85] offset:19200
	ds_write_b128 v155, v[86:89] offset:19264
	ds_write_b128 v155, v[90:93] offset:19328
	ds_write_b128 v155, v[94:97] offset:19392
	ds_write_b128 v155, v[102:105] offset:27648
	ds_write_b128 v155, v[98:101] offset:27712
	ds_write_b128 v155, v[106:109] offset:27776
	ds_write_b128 v155, v[110:113] offset:27840
	v_lshlrev_b64 v[50:51], 2, v[114:115]
	v_lshl_add_u64 v[74:75], s[12:13], 0, v[50:51]
	s_mov_b64 s[20:21], 0x5800
	v_lshl_add_u64 v[54:55], v[74:75], 0, s[20:21]
	s_mov_b64 s[20:21], 0xb000
	v_lshl_add_u64 v[56:57], v[74:75], 0, s[20:21]
	s_mov_b64 s[20:21], 0x8400
	v_lshl_add_u64 v[70:71], v[74:75], 0, s[20:21]
	s_mov_b64 s[20:21], 0xdc00
	v_lshl_add_u64 v[76:77], v[74:75], 0, s[20:21]
	s_movk_i32 s20, 0x5000
	v_lshl_add_u64 v[78:79], s[16:17], 0, v[50:51]
	s_mov_b64 s[14:15], 0x2c00
	v_add_co_u32_e32 v58, vcc, s20, v74
	v_lshl_add_u64 v[66:67], v[74:75], 0, s[14:15]
	v_lshl_add_u64 v[80:81], v[78:79], 0, s[14:15]
	v_addc_co_u32_e32 v59, vcc, 0, v75, vcc
	s_mov_b32 s14, 0xb000
	v_add_co_u32_e32 v60, vcc, s14, v74
	s_movk_i32 s15, 0x2000
	s_nop 0
	v_addc_co_u32_e32 v61, vcc, 0, v75, vcc
	v_add_co_u32_e32 v68, vcc, s15, v74
	s_mov_b32 s14, 0x8000
	s_nop 0
	v_addc_co_u32_e32 v69, vcc, 0, v75, vcc
	v_add_co_u32_e32 v72, vcc, s14, v74
	s_mov_b32 s20, 0xd000
	s_nop 0
	v_addc_co_u32_e32 v73, vcc, 0, v75, vcc
	s_waitcnt lgkmcnt(0)
	global_load_dwordx4 v[50:53], v[74:75], off offset:16
	global_load_dwordx4 v[86:89], v[74:75], off
	global_load_dwordx4 v[94:97], v[58:59], off offset:2048
	global_load_dwordx4 v[90:93], v[60:61], off
	s_nop 0
	global_load_dwordx4 v[58:61], v[54:55], off offset:16
	s_nop 0
	global_load_dwordx4 v[54:57], v[56:57], off offset:16
	s_nop 0
	global_load_dwordx4 v[62:65], v[78:79], off offset:16
	global_load_dwordx4 v[82:85], v[78:79], off
	v_add_co_u32_e32 v74, vcc, s20, v74
	global_load_dwordx4 v[98:101], v[68:69], off offset:3072
	global_load_dwordx4 v[102:105], v[72:73], off offset:1024
	s_nop 0
	global_load_dwordx4 v[66:69], v[66:67], off offset:16
	s_nop 0
	global_load_dwordx4 v[70:73], v[70:71], off offset:16
	v_addc_co_u32_e32 v75, vcc, 0, v75, vcc
	v_add_co_u32_e32 v78, vcc, s15, v78
	global_load_dwordx4 v[106:109], v[74:75], off offset:3072
	s_nop 0
	global_load_dwordx4 v[74:77], v[76:77], off offset:16
	v_addc_co_u32_e32 v79, vcc, 0, v79, vcc
	global_load_dwordx4 v[110:113], v[78:79], off offset:3072
	s_nop 0
	global_load_dwordx4 v[78:81], v[80:81], off offset:16
	s_barrier
	s_mulk_i32 s34, 0xfe
	v_readlane_b32 s14, v254, 51
	v_add_u32_e32 v158, s34, v140
	v_readlane_b32 s15, v254, 52
	v_cmp_gt_i32_e32 vcc, s24, v158
	s_movk_i32 s81, 0x2000
	v_lshl_add_u64 v[132:133], v[114:115], 1, s[14:15]
	s_and_b64 s[22:23], s[4:5], vcc
	s_waitcnt vmcnt(0)
	s_and_saveexec_b64 s[20:21], s[22:23]
	s_cbranch_execz .LBB0_1079
	v_add_u32_e32 v159, v151, v150
	v_cmp_gt_i32_e32 vcc, s39, v158
	s_nop 1
	v_cndmask_b32_e32 v114, v235, v236, vcc
	v_and_b32_e32 v115, v114, v158
	v_cmp_eq_u32_e64 s[100:101], 0, v115
	v_cmp_eq_u32_e32 vcc, v115, v114
	s_nop 3
	s_or_b64 s[100:101], s[100:101], vcc
	s_cbranch_scc0 .Lcf_0
	v_add_u32_e32 v159, v151, v150
	v_cmp_gt_i32_e32 vcc, s39, v158
	ds_read_b128 v[136:139], v159 offset:1904
	ds_read_b128 v[160:163], v159 offset:2432
	v_cndmask_b32_e32 v114, v235, v236, vcc
	v_and_b32_e32 v115, v114, v158
	ds_read_b128 v[164:167], v159 offset:2960
	ds_read_b128 v[168:171], v159 offset:1776
	v_cmp_eq_u32_e32 vcc, 0, v115
	s_waitcnt vmcnt(6) lgkmcnt(2)
	v_pk_mul_f32 v[116:117], v[102:103], v[160:161]
	v_pk_mul_f32 v[162:163], v[104:105], v[162:163]
	v_cndmask_b32_e64 v0, 1.0, 0, vcc
	v_cmp_eq_u32_e32 vcc, v115, v114
	v_pk_mul_f32 v[114:115], v[0:1], v[136:137] op_sel_hi:[0,1]
	v_pk_fma_f32 v[114:115], v[98:99], v[114:115], v[116:117]
	v_cndmask_b32_e64 v134, 1.0, 0, vcc
	s_waitcnt lgkmcnt(1)
	v_pk_mul_f32 v[116:117], v[134:135], v[164:165] op_sel_hi:[0,1]
	s_waitcnt vmcnt(3)
	v_pk_fma_f32 v[114:115], v[106:107], v[116:117], v[114:115]
	v_pk_mul_f32 v[138:139], v[0:1], v[138:139] op_sel_hi:[0,1]
	s_waitcnt vmcnt(1)
	v_pk_add_f32 v[136:137], v[110:111], v[114:115]
	v_pk_fma_f32 v[138:139], v[100:101], v[138:139], v[162:163]
	v_mul_f32_e32 v114, 0xbfb8aa3b, v136
	v_mul_f32_e32 v161, 0xbfb8aa3b, v137
	v_exp_f32_e32 v160, v114
	ds_read_b128 v[114:117], v159 offset:1792
	ds_read_b128 v[172:175], v159 offset:2304
	ds_read_b128 v[176:179], v159 offset:2832
	v_exp_f32_e32 v161, v161
	v_pk_mul_f32 v[162:163], v[134:135], v[166:167] op_sel_hi:[0,1]
	v_pk_fma_f32 v[138:139], v[108:109], v[162:163], v[138:139]
	v_add_f32_e32 v160, 1.0, v160
	v_pk_add_f32 v[138:139], v[112:113], v[138:139]
	s_waitcnt lgkmcnt(3)
	v_pk_mul_f32 v[164:165], v[0:1], v[168:169] op_sel_hi:[0,1]
	s_waitcnt lgkmcnt(1)
	v_pk_mul_f32 v[168:169], v[94:95], v[172:173]
	v_add_f32_e32 v161, 1.0, v161
	v_mul_f32_e32 v162, 0xbfb8aa3b, v138
	v_rcp_f32_e32 v160, v160
	v_pk_fma_f32 v[164:165], v[86:87], v[164:165], v[168:169]
	s_waitcnt lgkmcnt(0)
; DI unsigned pk2(float a, float b) { f32x2 v = {a, b}; bf16x2_t r = __builtin_convertvector(v, bf16x2_t); return __builtin_bit_cast(unsigned, r); }
; DI float silu_f(float g) { return g * rcpf_(1.f + ex2(-g * LOG2E)); }
; static __device__ __forceinline__ void phase_ffn_up(const P& p, int l, char* lds) {
;     ...
; #pragma unroll
;       for (int jj = 0; jj < 4; ++jj) {
;         const int r = (tid >> 3) + 64 * jj, tt = tstart + r;
;         if (r >= 1 && r <= 254 && tt < MEND) {
;           const int pos = tt < MLAT ? (tt & (TLAT - 1)) : ((tt - MLAT) & (TCTX - 1)), slen = tt < MLAT ? TLAT : TCTX;
;           const float fm = pos == 0 ? 0.f : 1.f, fp = pos == slen - 1 ? 0.f : 1.f;
;           const char* rp = tile + r * 528;
;           float o[8];
; #pragma unroll
;           for (int hf = 0; hf < 2; ++hf) {
;             const f32x4 am = *(const f32x4*)(rp - 528 + lca + hf * 16), a0 = *(const f32x4*)(rp + lca + hf * 16), ap = *(const f32x4*)(rp + 528 + lca + hf * 16);
;             const f32x4 gm = *(const f32x4*)(rp - 528 + lcg + hf * 16), g0 = *(const f32x4*)(rp + lcg + hf * 16), gp = *(const f32x4*)(rp + 528 + lcg + hf * 16);
; #pragma unroll
;             for (int e = 0; e < 4; ++e) {
;               const int q = hf * 4 + e;
;               const float ua = wa0[q] * (fm * am[e]) + wa1[q] * a0[e] + wa2[q] * (fp * ap[e]) + ba[q];
;               const float ug = wg0[q] * (fm * gm[e]) + wg1[q] * g0[e] + wg2[q] * (fp * gp[e]) + bg[q];
;               o[q] = silu_f(ug) * ua;
;             }
;           }
;           u32x4 w = {pk2(o[0], o[1]), pk2(o[2], o[3]), pk2(o[4], o[5]), pk2(o[6], o[7])};
;           *(u32x4*)(act + (size_t)tt * DFF + ca0) = w;
	v_pk_mul_f32 v[168:169], v[134:135], v[176:177] op_sel_hi:[0,1]
	v_rcp_f32_e32 v161, v161
	v_exp_f32_e32 v166, v162
	v_pk_fma_f32 v[164:165], v[90:91], v[168:169], v[164:165]
	v_pk_mul_f32 v[114:115], v[0:1], v[114:115] op_sel_hi:[0,1]
	v_pk_add_f32 v[162:163], v[82:83], v[164:165]
	v_mul_f32_e32 v164, 0xbfb8aa3b, v139
	v_exp_f32_e32 v164, v164
	v_pk_mul_f32 v[136:137], v[136:137], v[160:161]
	v_add_f32_e32 v160, 1.0, v166
	v_pk_mul_f32 v[136:137], v[162:163], v[136:137]
	v_rcp_f32_e32 v172, v160
	v_pk_mul_f32 v[160:161], v[0:1], v[170:171] op_sel_hi:[0,1]
	v_pk_mul_f32 v[162:163], v[96:97], v[174:175]
	v_pk_mul_f32 v[116:117], v[0:1], v[116:117] op_sel_hi:[0,1]
	v_pk_fma_f32 v[160:161], v[88:89], v[160:161], v[162:163]
	v_pk_mul_f32 v[162:163], v[134:135], v[178:179] op_sel_hi:[0,1]
	v_pk_fma_f32 v[168:169], v[92:93], v[162:163], v[160:161]
	v_add_f32_e32 v160, 1.0, v164
	v_rcp_f32_e32 v173, v160
	ds_read_b128 v[160:163], v159 offset:1920
	ds_read_b128 v[164:167], v159 offset:2448
	v_pk_add_f32 v[174:175], v[84:85], v[168:169]
	ds_read_b128 v[168:171], v159 offset:2976
	v_pk_mul_f32 v[138:139], v[138:139], v[172:173]
	s_waitcnt lgkmcnt(2)
	v_pk_mul_f32 v[160:161], v[0:1], v[160:161] op_sel_hi:[0,1]
	s_waitcnt lgkmcnt(1)
	v_pk_mul_f32 v[164:165], v[70:71], v[164:165]
	v_pk_mul_f32 v[138:139], v[174:175], v[138:139]
	v_pk_fma_f32 v[160:161], v[66:67], v[160:161], v[164:165]
	s_waitcnt lgkmcnt(0)
	v_pk_mul_f32 v[164:165], v[134:135], v[168:169] op_sel_hi:[0,1]
	v_pk_fma_f32 v[160:161], v[74:75], v[164:165], v[160:161]
	ds_read_b128 v[172:175], v159 offset:2320
	ds_read_b128 v[176:179], v159 offset:2848
	s_waitcnt vmcnt(0)
	v_pk_add_f32 v[160:161], v[78:79], v[160:161]
	v_pk_mul_f32 v[162:163], v[0:1], v[162:163] op_sel_hi:[0,1]
	v_mul_f32_e32 v164, 0xbfb8aa3b, v160
	v_exp_f32_e32 v164, v164
	s_waitcnt lgkmcnt(1)
	v_pk_mul_f32 v[168:169], v[58:59], v[172:173]
	v_pk_mul_f32 v[166:167], v[72:73], v[166:167]
	v_pk_fma_f32 v[114:115], v[50:51], v[114:115], v[168:169]
	v_add_f32_e32 v159, 1.0, v164
	v_rcp_f32_e32 v164, v159
	v_mul_f32_e32 v159, 0xbfb8aa3b, v161
	v_exp_f32_e32 v159, v159
	s_waitcnt lgkmcnt(0)
	v_pk_mul_f32 v[168:169], v[134:135], v[176:177] op_sel_hi:[0,1]
	v_pk_fma_f32 v[162:163], v[68:69], v[162:163], v[166:167]
	v_pk_mul_f32 v[166:167], v[134:135], v[170:171] op_sel_hi:[0,1]
	v_add_f32_e32 v159, 1.0, v159
	v_rcp_f32_e32 v165, v159
	v_pk_fma_f32 v[114:115], v[54:55], v[168:169], v[114:115]
	v_pk_fma_f32 v[162:163], v[76:77], v[166:167], v[162:163]
	v_pk_add_f32 v[114:115], v[62:63], v[114:115]
	v_pk_add_f32 v[162:163], v[80:81], v[162:163]
	v_pk_mul_f32 v[160:161], v[160:161], v[164:165]
	v_mul_f32_e32 v159, 0xbfb8aa3b, v162
	v_pk_mul_f32 v[160:161], v[114:115], v[160:161]
	v_mul_f32_e32 v115, 0xbfb8aa3b, v163
	v_exp_f32_e32 v159, v159
	v_exp_f32_e32 v115, v115
	v_pk_mul_f32 v[164:165], v[60:61], v[174:175]
	s_movk_i32 s14, 0x1600
	v_add_f32_e32 v114, 1.0, v159
	v_add_f32_e32 v0, 1.0, v115
	v_rcp_f32_e32 v114, v114
	v_rcp_f32_e32 v115, v0
	v_pk_fma_f32 v[116:117], v[52:53], v[116:117], v[164:165]
	v_pk_mul_f32 v[164:165], v[134:135], v[178:179] op_sel_hi:[0,1]
	v_pk_fma_f32 v[116:117], v[56:57], v[164:165], v[116:117]
	v_pk_mul_f32 v[114:115], v[162:163], v[114:115]
	v_pk_add_f32 v[116:117], v[64:65], v[116:117]
	s_nop 0
	v_pk_mul_f32 v[162:163], v[116:117], v[114:115]
	v_cvt_pk_bf16_f32 v114, v136, v137
	v_cvt_pk_bf16_f32 v115, v138, v139
	v_cvt_pk_bf16_f32 v116, v160, v161
	v_cvt_pk_bf16_f32 v117, v162, v163
	v_mad_i64_i32 v[136:137], s[22:23], v158, s14, v[132:133]
	global_store_dwordx4 v[136:137], v[114:117], off sc0 sc1 nt
.LBB0_1079:
	s_or_b64 exec, exec, s[20:21]
	v_add_u32_e32 v159, 64, v158
	v_cmp_gt_i32_e32 vcc, s24, v159
	s_and_b64 s[22:23], s[6:7], vcc
	s_and_saveexec_b64 s[20:21], s[22:23]
	s_cbranch_execz .LBB0_1081
	v_cmp_gt_i32_e32 vcc, s39, v159
	s_nop 1
	v_cndmask_b32_e32 v114, v235, v236, vcc
	v_and_b32_e32 v115, v114, v159
	v_cmp_eq_u32_e64 s[100:101], 0, v115
	v_cmp_eq_u32_e32 vcc, v115, v114
	s_nop 3
	s_or_b64 s[100:101], s[100:101], vcc
	s_cbranch_scc0 .Lcf_1
	v_cmp_gt_i32_e32 vcc, s39, v159
	ds_read_b128 v[136:139], v156 offset:1904
	ds_read_b128 v[160:163], v156 offset:2432
	v_cndmask_b32_e32 v114, v235, v236, vcc
	v_and_b32_e32 v115, v114, v159
	ds_read_b128 v[164:167], v156 offset:2960
	ds_read_b128 v[168:171], v156 offset:1776
	v_cmp_eq_u32_e32 vcc, 0, v115
	s_waitcnt lgkmcnt(2)
	v_pk_mul_f32 v[116:117], v[102:103], v[160:161]
	v_pk_mul_f32 v[162:163], v[104:105], v[162:163]
	v_cndmask_b32_e64 v0, 1.0, 0, vcc
	v_cmp_eq_u32_e32 vcc, v115, v114
	v_pk_mul_f32 v[114:115], v[0:1], v[136:137] op_sel_hi:[0,1]
	v_pk_fma_f32 v[114:115], v[98:99], v[114:115], v[116:117]
	v_cndmask_b32_e64 v134, 1.0, 0, vcc
	s_waitcnt lgkmcnt(1)
	v_pk_mul_f32 v[116:117], v[134:135], v[164:165] op_sel_hi:[0,1]
	v_pk_fma_f32 v[114:115], v[106:107], v[116:117], v[114:115]
	v_pk_mul_f32 v[138:139], v[0:1], v[138:139] op_sel_hi:[0,1]
	v_pk_add_f32 v[136:137], v[110:111], v[114:115]
	v_pk_fma_f32 v[138:139], v[100:101], v[138:139], v[162:163]
	v_mul_f32_e32 v114, 0xbfb8aa3b, v136
	v_mul_f32_e32 v161, 0xbfb8aa3b, v137
	v_exp_f32_e32 v160, v114
	ds_read_b128 v[114:117], v156 offset:1792
	ds_read_b128 v[172:175], v156 offset:2304
	ds_read_b128 v[176:179], v156 offset:2832
	v_exp_f32_e32 v161, v161
	v_pk_mul_f32 v[162:163], v[134:135], v[166:167] op_sel_hi:[0,1]
	v_pk_fma_f32 v[138:139], v[108:109], v[162:163], v[138:139]
	v_add_f32_e32 v160, 1.0, v160
	v_pk_add_f32 v[138:139], v[112:113], v[138:139]
	s_waitcnt lgkmcnt(3)
	v_pk_mul_f32 v[164:165], v[0:1], v[168:169] op_sel_hi:[0,1]
	s_waitcnt lgkmcnt(1)
; DI unsigned pk2(float a, float b) { f32x2 v = {a, b}; bf16x2_t r = __builtin_convertvector(v, bf16x2_t); return __builtin_bit_cast(unsigned, r); }
; DI float silu_f(float g) { return g * rcpf_(1.f + ex2(-g * LOG2E)); }
; static __device__ __forceinline__ void phase_ffn_up(const P& p, int l, char* lds) {
;     ...
; #pragma unroll
;       for (int jj = 0; jj < 4; ++jj) {
;         const int r = (tid >> 3) + 64 * jj, tt = tstart + r;
;         if (r >= 1 && r <= 254 && tt < MEND) {
;           const int pos = tt < MLAT ? (tt & (TLAT - 1)) : ((tt - MLAT) & (TCTX - 1)), slen = tt < MLAT ? TLAT : TCTX;
;           const float fm = pos == 0 ? 0.f : 1.f, fp = pos == slen - 1 ? 0.f : 1.f;
;           const char* rp = tile + r * 528;
;           float o[8];
; #pragma unroll
;           for (int hf = 0; hf < 2; ++hf) {
;             const f32x4 am = *(const f32x4*)(rp - 528 + lca + hf * 16), a0 = *(const f32x4*)(rp + lca + hf * 16), ap = *(const f32x4*)(rp + 528 + lca + hf * 16);
;             const f32x4 gm = *(const f32x4*)(rp - 528 + lcg + hf * 16), g0 = *(const f32x4*)(rp + lcg + hf * 16), gp = *(const f32x4*)(rp + 528 + lcg + hf * 16);
; #pragma unroll
;             for (int e = 0; e < 4; ++e) {
;               const int q = hf * 4 + e;
;               const float ua = wa0[q] * (fm * am[e]) + wa1[q] * a0[e] + wa2[q] * (fp * ap[e]) + ba[q];
;               const float ug = wg0[q] * (fm * gm[e]) + wg1[q] * g0[e] + wg2[q] * (fp * gp[e]) + bg[q];
;               o[q] = silu_f(ug) * ua;
;             }
;           }
;           u32x4 w = {pk2(o[0], o[1]), pk2(o[2], o[3]), pk2(o[4], o[5]), pk2(o[6], o[7])};
;           *(u32x4*)(act + (size_t)tt * DFF + ca0) = w;
	v_pk_mul_f32 v[168:169], v[94:95], v[172:173]
	v_add_f32_e32 v161, 1.0, v161
	v_mul_f32_e32 v162, 0xbfb8aa3b, v138
	v_rcp_f32_e32 v160, v160
	v_pk_fma_f32 v[164:165], v[86:87], v[164:165], v[168:169]
	s_waitcnt lgkmcnt(0)
	v_pk_mul_f32 v[168:169], v[134:135], v[176:177] op_sel_hi:[0,1]
	v_rcp_f32_e32 v161, v161
	v_exp_f32_e32 v166, v162
	v_pk_fma_f32 v[164:165], v[90:91], v[168:169], v[164:165]
	v_pk_mul_f32 v[114:115], v[0:1], v[114:115] op_sel_hi:[0,1]
	v_pk_add_f32 v[162:163], v[82:83], v[164:165]
	v_mul_f32_e32 v164, 0xbfb8aa3b, v139
	v_exp_f32_e32 v164, v164
	v_pk_mul_f32 v[136:137], v[136:137], v[160:161]
	v_add_f32_e32 v160, 1.0, v166
	v_pk_mul_f32 v[136:137], v[162:163], v[136:137]
	v_rcp_f32_e32 v172, v160
	v_pk_mul_f32 v[160:161], v[0:1], v[170:171] op_sel_hi:[0,1]
	v_pk_mul_f32 v[162:163], v[96:97], v[174:175]
	v_pk_mul_f32 v[116:117], v[0:1], v[116:117] op_sel_hi:[0,1]
	v_pk_fma_f32 v[160:161], v[88:89], v[160:161], v[162:163]
	v_pk_mul_f32 v[162:163], v[134:135], v[178:179] op_sel_hi:[0,1]
	v_pk_fma_f32 v[168:169], v[92:93], v[162:163], v[160:161]
	v_add_f32_e32 v160, 1.0, v164
	v_rcp_f32_e32 v173, v160
	ds_read_b128 v[160:163], v156 offset:1920
	ds_read_b128 v[164:167], v156 offset:2448
	v_pk_add_f32 v[174:175], v[84:85], v[168:169]
	ds_read_b128 v[168:171], v156 offset:2976
	v_pk_mul_f32 v[138:139], v[138:139], v[172:173]
	s_waitcnt lgkmcnt(2)
	v_pk_mul_f32 v[160:161], v[0:1], v[160:161] op_sel_hi:[0,1]
	s_waitcnt lgkmcnt(1)
	v_pk_mul_f32 v[164:165], v[70:71], v[164:165]
	v_pk_mul_f32 v[138:139], v[174:175], v[138:139]
	v_pk_fma_f32 v[160:161], v[66:67], v[160:161], v[164:165]
	s_waitcnt lgkmcnt(0)
	v_pk_mul_f32 v[164:165], v[134:135], v[168:169] op_sel_hi:[0,1]
	v_pk_fma_f32 v[160:161], v[74:75], v[164:165], v[160:161]
	ds_read_b128 v[172:175], v156 offset:2320
	ds_read_b128 v[176:179], v156 offset:2848
	v_pk_add_f32 v[160:161], v[78:79], v[160:161]
	v_pk_mul_f32 v[162:163], v[0:1], v[162:163] op_sel_hi:[0,1]
	v_mul_f32_e32 v164, 0xbfb8aa3b, v160
	v_mul_f32_e32 v165, 0xbfb8aa3b, v161
	v_exp_f32_e32 v164, v164
	v_exp_f32_e32 v165, v165
	s_waitcnt lgkmcnt(1)
	v_pk_mul_f32 v[168:169], v[58:59], v[172:173]
	v_pk_mul_f32 v[166:167], v[72:73], v[166:167]
	v_add_f32_e32 v164, 1.0, v164
	v_add_f32_e32 v165, 1.0, v165
	v_rcp_f32_e32 v164, v164
	v_rcp_f32_e32 v165, v165
	v_pk_fma_f32 v[114:115], v[50:51], v[114:115], v[168:169]
	s_waitcnt lgkmcnt(0)
	v_pk_mul_f32 v[168:169], v[134:135], v[176:177] op_sel_hi:[0,1]
	v_pk_fma_f32 v[162:163], v[68:69], v[162:163], v[166:167]
	v_pk_mul_f32 v[166:167], v[134:135], v[170:171] op_sel_hi:[0,1]
	v_pk_fma_f32 v[114:115], v[54:55], v[168:169], v[114:115]
	v_pk_fma_f32 v[162:163], v[76:77], v[166:167], v[162:163]
	v_pk_add_f32 v[114:115], v[62:63], v[114:115]
	v_pk_add_f32 v[162:163], v[80:81], v[162:163]
	v_pk_mul_f32 v[160:161], v[160:161], v[164:165]
	v_mul_f32_e32 v166, 0xbfb8aa3b, v162
	v_pk_mul_f32 v[160:161], v[114:115], v[160:161]
	v_mul_f32_e32 v115, 0xbfb8aa3b, v163
	v_exp_f32_e32 v166, v166
	v_exp_f32_e32 v115, v115
	v_pk_mul_f32 v[164:165], v[60:61], v[174:175]
	s_movk_i32 s14, 0x1600
	v_add_f32_e32 v114, 1.0, v166
	v_add_f32_e32 v0, 1.0, v115
	v_rcp_f32_e32 v114, v114
	v_rcp_f32_e32 v115, v0
	v_pk_fma_f32 v[116:117], v[52:53], v[116:117], v[164:165]
	v_pk_mul_f32 v[164:165], v[134:135], v[178:179] op_sel_hi:[0,1]
	v_pk_fma_f32 v[116:117], v[56:57], v[164:165], v[116:117]
	v_pk_mul_f32 v[114:115], v[162:163], v[114:115]
	v_pk_add_f32 v[116:117], v[64:65], v[116:117]
	s_nop 0
	v_pk_mul_f32 v[162:163], v[116:117], v[114:115]
	v_cvt_pk_bf16_f32 v114, v136, v137
	v_cvt_pk_bf16_f32 v115, v138, v139
	v_cvt_pk_bf16_f32 v116, v160, v161
	v_cvt_pk_bf16_f32 v117, v162, v163
	v_mad_i64_i32 v[136:137], s[22:23], v159, s14, v[132:133]
	global_store_dwordx4 v[136:137], v[114:117], off sc0 sc1 nt
.LBB0_1081:
	s_or_b64 exec, exec, s[20:21]
	v_add_u32_e32 v159, 0x80, v158
	v_cmp_gt_i32_e32 vcc, s24, v159
	s_and_b64 s[22:23], s[8:9], vcc
	s_and_saveexec_b64 s[20:21], s[22:23]
	s_cbranch_execz .LBB0_1083
	v_cmp_gt_i32_e32 vcc, s39, v159
	s_nop 1
	v_cndmask_b32_e32 v114, v235, v236, vcc
	v_and_b32_e32 v115, v114, v159
	v_cmp_eq_u32_e64 s[100:101], 0, v115
	v_cmp_eq_u32_e32 vcc, v115, v114
	s_nop 3
	s_or_b64 s[100:101], s[100:101], vcc
	s_cbranch_scc0 .Lcf_2
; DI unsigned pk2(float a, float b) { f32x2 v = {a, b}; bf16x2_t r = __builtin_convertvector(v, bf16x2_t); return __builtin_bit_cast(unsigned, r); }
; DI float silu_f(float g) { return g * rcpf_(1.f + ex2(-g * LOG2E)); }
; static __device__ __forceinline__ void phase_ffn_up(const P& p, int l, char* lds) {
;     ...
; #pragma unroll
;       for (int jj = 0; jj < 4; ++jj) {
;         const int r = (tid >> 3) + 64 * jj, tt = tstart + r;
;         if (r >= 1 && r <= 254 && tt < MEND) {
;           const int pos = tt < MLAT ? (tt & (TLAT - 1)) : ((tt - MLAT) & (TCTX - 1)), slen = tt < MLAT ? TLAT : TCTX;
;           const float fm = pos == 0 ? 0.f : 1.f, fp = pos == slen - 1 ? 0.f : 1.f;
;           const char* rp = tile + r * 528;
;           float o[8];
; #pragma unroll
;           for (int hf = 0; hf < 2; ++hf) {
;             const f32x4 am = *(const f32x4*)(rp - 528 + lca + hf * 16), a0 = *(const f32x4*)(rp + lca + hf * 16), ap = *(const f32x4*)(rp + 528 + lca + hf * 16);
;             const f32x4 gm = *(const f32x4*)(rp - 528 + lcg + hf * 16), g0 = *(const f32x4*)(rp + lcg + hf * 16), gp = *(const f32x4*)(rp + 528 + lcg + hf * 16);
; #pragma unroll
;             for (int e = 0; e < 4; ++e) {
;               const int q = hf * 4 + e;
;               const float ua = wa0[q] * (fm * am[e]) + wa1[q] * a0[e] + wa2[q] * (fp * ap[e]) + ba[q];
;               const float ug = wg0[q] * (fm * gm[e]) + wg1[q] * g0[e] + wg2[q] * (fp * gp[e]) + bg[q];
;               o[q] = silu_f(ug) * ua;
;             }
;           }
;           u32x4 w = {pk2(o[0], o[1]), pk2(o[2], o[3]), pk2(o[4], o[5]), pk2(o[6], o[7])};
;           *(u32x4*)(act + (size_t)tt * DFF + ca0) = w;
	v_cmp_gt_i32_e32 vcc, s39, v159
	ds_read_b128 v[136:139], v157 offset:1904
	ds_read_b128 v[160:163], v157 offset:2432
	v_cndmask_b32_e32 v114, v235, v236, vcc
	v_and_b32_e32 v115, v114, v159
	ds_read_b128 v[164:167], v157 offset:2960
	ds_read_b128 v[168:171], v157 offset:1776
	v_cmp_eq_u32_e32 vcc, 0, v115
	s_waitcnt lgkmcnt(2)
	v_pk_mul_f32 v[116:117], v[102:103], v[160:161]
	v_pk_mul_f32 v[162:163], v[104:105], v[162:163]
	v_cndmask_b32_e64 v0, 1.0, 0, vcc
	v_cmp_eq_u32_e32 vcc, v115, v114
	v_pk_mul_f32 v[114:115], v[0:1], v[136:137] op_sel_hi:[0,1]
	v_pk_fma_f32 v[114:115], v[98:99], v[114:115], v[116:117]
	v_cndmask_b32_e64 v134, 1.0, 0, vcc
	s_waitcnt lgkmcnt(1)
	v_pk_mul_f32 v[116:117], v[134:135], v[164:165] op_sel_hi:[0,1]
	v_pk_fma_f32 v[114:115], v[106:107], v[116:117], v[114:115]
	v_pk_mul_f32 v[138:139], v[0:1], v[138:139] op_sel_hi:[0,1]
	v_pk_add_f32 v[136:137], v[110:111], v[114:115]
	v_pk_fma_f32 v[138:139], v[100:101], v[138:139], v[162:163]
	v_mul_f32_e32 v114, 0xbfb8aa3b, v136
	v_mul_f32_e32 v161, 0xbfb8aa3b, v137
	v_exp_f32_e32 v160, v114
	ds_read_b128 v[114:117], v157 offset:1792
	ds_read_b128 v[172:175], v157 offset:2304
	ds_read_b128 v[176:179], v157 offset:2832
	v_exp_f32_e32 v161, v161
	v_pk_mul_f32 v[162:163], v[134:135], v[166:167] op_sel_hi:[0,1]
	v_pk_fma_f32 v[138:139], v[108:109], v[162:163], v[138:139]
	v_add_f32_e32 v160, 1.0, v160
	v_pk_add_f32 v[138:139], v[112:113], v[138:139]
	s_waitcnt lgkmcnt(3)
	v_pk_mul_f32 v[164:165], v[0:1], v[168:169] op_sel_hi:[0,1]
	s_waitcnt lgkmcnt(1)
	v_pk_mul_f32 v[168:169], v[94:95], v[172:173]
	v_add_f32_e32 v161, 1.0, v161
	v_mul_f32_e32 v162, 0xbfb8aa3b, v138
	v_rcp_f32_e32 v160, v160
	v_pk_fma_f32 v[164:165], v[86:87], v[164:165], v[168:169]
	s_waitcnt lgkmcnt(0)
	v_pk_mul_f32 v[168:169], v[134:135], v[176:177] op_sel_hi:[0,1]
	v_rcp_f32_e32 v161, v161
	v_exp_f32_e32 v166, v162
	v_pk_fma_f32 v[164:165], v[90:91], v[168:169], v[164:165]
	v_pk_mul_f32 v[114:115], v[0:1], v[114:115] op_sel_hi:[0,1]
	v_pk_add_f32 v[162:163], v[82:83], v[164:165]
	v_mul_f32_e32 v164, 0xbfb8aa3b, v139
	v_exp_f32_e32 v164, v164
	v_pk_mul_f32 v[136:137], v[136:137], v[160:161]
	v_add_f32_e32 v160, 1.0, v166
	v_pk_mul_f32 v[136:137], v[162:163], v[136:137]
	v_rcp_f32_e32 v172, v160
	v_pk_mul_f32 v[160:161], v[0:1], v[170:171] op_sel_hi:[0,1]
	v_pk_mul_f32 v[162:163], v[96:97], v[174:175]
	v_pk_mul_f32 v[116:117], v[0:1], v[116:117] op_sel_hi:[0,1]
	v_pk_fma_f32 v[160:161], v[88:89], v[160:161], v[162:163]
	v_pk_mul_f32 v[162:163], v[134:135], v[178:179] op_sel_hi:[0,1]
	v_pk_fma_f32 v[168:169], v[92:93], v[162:163], v[160:161]
	v_add_f32_e32 v160, 1.0, v164
	v_rcp_f32_e32 v173, v160
	ds_read_b128 v[160:163], v157 offset:1920
	ds_read_b128 v[164:167], v157 offset:2448
	v_pk_add_f32 v[174:175], v[84:85], v[168:169]
	ds_read_b128 v[168:171], v157 offset:2976
	v_pk_mul_f32 v[138:139], v[138:139], v[172:173]
	s_waitcnt lgkmcnt(2)
	v_pk_mul_f32 v[160:161], v[0:1], v[160:161] op_sel_hi:[0,1]
	s_waitcnt lgkmcnt(1)
	v_pk_mul_f32 v[164:165], v[70:71], v[164:165]
	v_pk_mul_f32 v[138:139], v[174:175], v[138:139]
	v_pk_fma_f32 v[160:161], v[66:67], v[160:161], v[164:165]
	s_waitcnt lgkmcnt(0)
	v_pk_mul_f32 v[164:165], v[134:135], v[168:169] op_sel_hi:[0,1]
	v_pk_fma_f32 v[160:161], v[74:75], v[164:165], v[160:161]
	ds_read_b128 v[172:175], v157 offset:2320
	ds_read_b128 v[176:179], v157 offset:2848
	v_pk_add_f32 v[160:161], v[78:79], v[160:161]
	v_pk_mul_f32 v[162:163], v[0:1], v[162:163] op_sel_hi:[0,1]
	v_mul_f32_e32 v164, 0xbfb8aa3b, v160
	v_mul_f32_e32 v165, 0xbfb8aa3b, v161
	v_exp_f32_e32 v164, v164
	v_exp_f32_e32 v165, v165
	s_waitcnt lgkmcnt(1)
	v_pk_mul_f32 v[168:169], v[58:59], v[172:173]
	v_pk_mul_f32 v[166:167], v[72:73], v[166:167]
	v_add_f32_e32 v164, 1.0, v164
	v_add_f32_e32 v165, 1.0, v165
	v_rcp_f32_e32 v164, v164
	v_rcp_f32_e32 v165, v165
	v_pk_fma_f32 v[114:115], v[50:51], v[114:115], v[168:169]
	s_waitcnt lgkmcnt(0)
	v_pk_mul_f32 v[168:169], v[134:135], v[176:177] op_sel_hi:[0,1]
	v_pk_fma_f32 v[162:163], v[68:69], v[162:163], v[166:167]
	v_pk_mul_f32 v[166:167], v[134:135], v[170:171] op_sel_hi:[0,1]
	v_pk_fma_f32 v[114:115], v[54:55], v[168:169], v[114:115]
	v_pk_fma_f32 v[162:163], v[76:77], v[166:167], v[162:163]
	v_pk_add_f32 v[114:115], v[62:63], v[114:115]
	v_pk_add_f32 v[162:163], v[80:81], v[162:163]
	v_pk_mul_f32 v[160:161], v[160:161], v[164:165]
	v_mul_f32_e32 v166, 0xbfb8aa3b, v162
	v_pk_mul_f32 v[160:161], v[114:115], v[160:161]
	v_mul_f32_e32 v115, 0xbfb8aa3b, v163
	v_exp_f32_e32 v166, v166
	v_exp_f32_e32 v115, v115
	v_pk_mul_f32 v[164:165], v[60:61], v[174:175]
	s_movk_i32 s14, 0x1600
	v_add_f32_e32 v114, 1.0, v166
	v_add_f32_e32 v0, 1.0, v115
	v_rcp_f32_e32 v114, v114
	v_rcp_f32_e32 v115, v0
	v_pk_fma_f32 v[116:117], v[52:53], v[116:117], v[164:165]
	v_pk_mul_f32 v[164:165], v[134:135], v[178:179] op_sel_hi:[0,1]
	v_pk_fma_f32 v[116:117], v[56:57], v[164:165], v[116:117]
	v_pk_mul_f32 v[114:115], v[162:163], v[114:115]
	v_pk_add_f32 v[116:117], v[64:65], v[116:117]
	s_nop 0
	v_pk_mul_f32 v[162:163], v[116:117], v[114:115]
	v_cvt_pk_bf16_f32 v114, v136, v137
	v_cvt_pk_bf16_f32 v115, v138, v139
	v_cvt_pk_bf16_f32 v116, v160, v161
	v_cvt_pk_bf16_f32 v117, v162, v163
	v_mad_i64_i32 v[136:137], s[22:23], v159, s14, v[132:133]
	global_store_dwordx4 v[136:137], v[114:117], off sc0 sc1 nt
; DI unsigned pk2(float a, float b) { f32x2 v = {a, b}; bf16x2_t r = __builtin_convertvector(v, bf16x2_t); return __builtin_bit_cast(unsigned, r); }
; DI float silu_f(float g) { return g * rcpf_(1.f + ex2(-g * LOG2E)); }
; static __device__ __forceinline__ void phase_ffn_up(const P& p, int l, char* lds) {
;     ...
; #pragma unroll
;       for (int jj = 0; jj < 4; ++jj) {
;         const int r = (tid >> 3) + 64 * jj, tt = tstart + r;
;         if (r >= 1 && r <= 254 && tt < MEND) {
;           const int pos = tt < MLAT ? (tt & (TLAT - 1)) : ((tt - MLAT) & (TCTX - 1)), slen = tt < MLAT ? TLAT : TCTX;
;           const float fm = pos == 0 ? 0.f : 1.f, fp = pos == slen - 1 ? 0.f : 1.f;
;           const char* rp = tile + r * 528;
;           float o[8];
; #pragma unroll
;           for (int hf = 0; hf < 2; ++hf) {
;             const f32x4 am = *(const f32x4*)(rp - 528 + lca + hf * 16), a0 = *(const f32x4*)(rp + lca + hf * 16), ap = *(const f32x4*)(rp + 528 + lca + hf * 16);
;             const f32x4 gm = *(const f32x4*)(rp - 528 + lcg + hf * 16), g0 = *(const f32x4*)(rp + lcg + hf * 16), gp = *(const f32x4*)(rp + 528 + lcg + hf * 16);
; #pragma unroll
;             for (int e = 0; e < 4; ++e) {
;               const int q = hf * 4 + e;
;               const float ua = wa0[q] * (fm * am[e]) + wa1[q] * a0[e] + wa2[q] * (fp * ap[e]) + ba[q];
;               const float ug = wg0[q] * (fm * gm[e]) + wg1[q] * g0[e] + wg2[q] * (fp * gp[e]) + bg[q];
;               o[q] = silu_f(ug) * ua;
;             }
;           }
;           u32x4 w = {pk2(o[0], o[1]), pk2(o[2], o[3]), pk2(o[4], o[5]), pk2(o[6], o[7])};
;           *(u32x4*)(act + (size_t)tt * DFF + ca0) = w;
.LBB0_1083:
	s_or_b64 exec, exec, s[20:21]
	v_add_u32_e32 v136, 0xc0, v158
	v_cmp_gt_i32_e32 vcc, s24, v136
	s_and_b64 s[22:23], s[10:11], vcc
	s_and_saveexec_b64 s[20:21], s[22:23]
	s_cbranch_execz .LBB0_1058
	v_cmp_gt_i32_e32 vcc, s39, v136
	s_nop 1
	v_cndmask_b32_e32 v114, v235, v236, vcc
	v_and_b32_e32 v115, v114, v136
	v_cmp_eq_u32_e64 s[100:101], 0, v115
	v_cmp_eq_u32_e32 vcc, v115, v114
	s_nop 3
	s_or_b64 s[100:101], s[100:101], vcc
	s_cbranch_scc0 .Lcf_3
	v_cmp_gt_i32_e32 vcc, s39, v136
	ds_read_b128 v[158:161], v157 offset:35696
	ds_read_b128 v[162:165], v157 offset:36224
	v_cndmask_b32_e32 v114, v235, v236, vcc
	v_and_b32_e32 v115, v114, v136
	ds_read_b128 v[166:169], v157 offset:36752
	ds_read_b128 v[170:173], v157 offset:35568
	v_cmp_eq_u32_e32 vcc, 0, v115
	s_waitcnt lgkmcnt(2)
	v_pk_mul_f32 v[102:103], v[102:103], v[162:163]
	s_movk_i32 s14, 0x1600
	v_cndmask_b32_e64 v0, 1.0, 0, vcc
	v_cmp_eq_u32_e32 vcc, v115, v114
	v_pk_mul_f32 v[114:115], v[0:1], v[158:159] op_sel_hi:[0,1]
	v_pk_fma_f32 v[98:99], v[98:99], v[114:115], v[102:103]
	v_cndmask_b32_e64 v134, 1.0, 0, vcc
	s_waitcnt lgkmcnt(1)
	v_pk_mul_f32 v[102:103], v[134:135], v[166:167] op_sel_hi:[0,1]
	v_pk_fma_f32 v[98:99], v[106:107], v[102:103], v[98:99]
	ds_read_b128 v[114:117], v157 offset:35584
	ds_read_b128 v[174:177], v157 offset:36096
	ds_read_b128 v[178:181], v157 offset:36624
	v_pk_add_f32 v[98:99], v[110:111], v[98:99]
	s_waitcnt lgkmcnt(3)
	v_pk_mul_f32 v[106:107], v[0:1], v[170:171] op_sel_hi:[0,1]
	v_mul_f32_e32 v103, 0xbfb8aa3b, v99
	v_exp_f32_e32 v103, v103
	s_waitcnt lgkmcnt(1)
	v_pk_mul_f32 v[94:95], v[94:95], v[174:175]
	v_mul_f32_e32 v102, 0xbfb8aa3b, v98
	v_pk_fma_f32 v[86:87], v[86:87], v[106:107], v[94:95]
	s_waitcnt lgkmcnt(0)
	v_pk_mul_f32 v[94:95], v[134:135], v[178:179] op_sel_hi:[0,1]
	v_exp_f32_e32 v102, v102
	v_pk_fma_f32 v[86:87], v[90:91], v[94:95], v[86:87]
	v_add_f32_e32 v90, 1.0, v103
	v_rcp_f32_e32 v103, v90
	v_pk_mul_f32 v[90:91], v[0:1], v[160:161] op_sel_hi:[0,1]
	v_pk_mul_f32 v[94:95], v[104:105], v[164:165]
	v_add_f32_e32 v102, 1.0, v102
	v_pk_fma_f32 v[90:91], v[100:101], v[90:91], v[94:95]
	v_pk_mul_f32 v[94:95], v[134:135], v[168:169] op_sel_hi:[0,1]
	v_pk_fma_f32 v[90:91], v[108:109], v[94:95], v[90:91]
	v_rcp_f32_e32 v102, v102
	v_pk_add_f32 v[100:101], v[112:113], v[90:91]
	v_pk_add_f32 v[82:83], v[82:83], v[86:87]
	v_mul_f32_e32 v90, 0xbfb8aa3b, v100
	v_exp_f32_e32 v90, v90
	v_pk_mul_f32 v[86:87], v[98:99], v[102:103]
	v_mul_f32_e32 v94, 0xbfb8aa3b, v101
	v_pk_mul_f32 v[82:83], v[82:83], v[86:87]
	v_add_f32_e32 v86, 1.0, v90
	v_pk_mul_f32 v[90:91], v[96:97], v[176:177]
	v_exp_f32_e32 v96, v94
	v_rcp_f32_e32 v98, v86
	v_pk_mul_f32 v[86:87], v[0:1], v[172:173] op_sel_hi:[0,1]
	v_pk_fma_f32 v[86:87], v[88:89], v[86:87], v[90:91]
	v_pk_mul_f32 v[88:89], v[134:135], v[180:181] op_sel_hi:[0,1]
	v_pk_fma_f32 v[94:95], v[92:93], v[88:89], v[86:87]
	v_add_f32_e32 v86, 1.0, v96
	v_rcp_f32_e32 v99, v86
	ds_read_b128 v[86:89], v157 offset:35712
	ds_read_b128 v[90:93], v157 offset:36240
	v_pk_add_f32 v[84:85], v[84:85], v[94:95]
	ds_read_b128 v[94:97], v157 offset:36768
	v_pk_mul_f32 v[98:99], v[100:101], v[98:99]
	s_waitcnt lgkmcnt(2)
	v_pk_mul_f32 v[86:87], v[0:1], v[86:87] op_sel_hi:[0,1]
	s_waitcnt lgkmcnt(1)
	v_pk_mul_f32 v[70:71], v[70:71], v[90:91]
	s_nop 0
	v_pk_fma_f32 v[66:67], v[66:67], v[86:87], v[70:71]
	s_waitcnt lgkmcnt(0)
	v_pk_mul_f32 v[70:71], v[134:135], v[94:95] op_sel_hi:[0,1]
	v_pk_fma_f32 v[66:67], v[74:75], v[70:71], v[66:67]
	v_pk_add_f32 v[70:71], v[78:79], v[66:67]
	v_pk_mul_f32 v[78:79], v[0:1], v[114:115] op_sel_hi:[0,1]
	v_mul_f32_e32 v66, 0xbfb8aa3b, v70
	v_exp_f32_e32 v74, v66
	v_pk_mul_f32 v[66:67], v[84:85], v[98:99]
	ds_read_b128 v[84:87], v157 offset:36112
	ds_read_b128 v[98:101], v157 offset:36640
	v_mul_f32_e32 v75, 0xbfb8aa3b, v71
	v_exp_f32_e32 v75, v75
	v_add_f32_e32 v74, 1.0, v74
	s_waitcnt lgkmcnt(1)
	v_pk_mul_f32 v[58:59], v[58:59], v[84:85]
	v_rcp_f32_e32 v74, v74
	v_pk_fma_f32 v[50:51], v[50:51], v[78:79], v[58:59]
	s_waitcnt lgkmcnt(0)
	v_pk_mul_f32 v[58:59], v[134:135], v[98:99] op_sel_hi:[0,1]
	v_pk_fma_f32 v[50:51], v[54:55], v[58:59], v[50:51]
	v_add_f32_e32 v54, 1.0, v75
	v_rcp_f32_e32 v75, v54
	v_pk_mul_f32 v[54:55], v[0:1], v[88:89] op_sel_hi:[0,1]
	v_pk_mul_f32 v[58:59], v[72:73], v[92:93]
	v_pk_add_f32 v[50:51], v[62:63], v[50:51]
	v_pk_fma_f32 v[54:55], v[68:69], v[54:55], v[58:59]
	v_pk_mul_f32 v[58:59], v[134:135], v[96:97] op_sel_hi:[0,1]
	v_pk_fma_f32 v[54:55], v[76:77], v[58:59], v[54:55]
	v_pk_mul_f32 v[62:63], v[0:1], v[116:117] op_sel_hi:[0,1]
	v_pk_add_f32 v[54:55], v[80:81], v[54:55]
	v_pk_mul_f32 v[60:61], v[60:61], v[86:87]
	v_mul_f32_e32 v58, 0xbfb8aa3b, v54
	v_exp_f32_e32 v68, v58
	v_pk_mul_f32 v[58:59], v[70:71], v[74:75]
	v_pk_fma_f32 v[52:53], v[52:53], v[62:63], v[60:61]
	v_pk_mul_f32 v[58:59], v[50:51], v[58:59]
	v_mul_f32_e32 v51, 0xbfb8aa3b, v55
	v_exp_f32_e32 v51, v51
	v_add_f32_e32 v50, 1.0, v68
	v_rcp_f32_e32 v50, v50
	v_pk_mul_f32 v[60:61], v[134:135], v[100:101] op_sel_hi:[0,1]
	v_add_f32_e32 v0, 1.0, v51
	v_rcp_f32_e32 v51, v0
	v_pk_fma_f32 v[52:53], v[56:57], v[60:61], v[52:53]
	v_pk_mul_f32 v[50:51], v[54:55], v[50:51]
	v_pk_add_f32 v[52:53], v[64:65], v[52:53]
	s_nop 0
	v_pk_mul_f32 v[54:55], v[52:53], v[50:51]
	v_cvt_pk_bf16_f32 v50, v82, v83
	v_cvt_pk_bf16_f32 v51, v66, v67
	v_cvt_pk_bf16_f32 v52, v58, v59
	v_cvt_pk_bf16_f32 v53, v54, v55
	v_mad_i64_i32 v[54:55], s[22:23], v136, s14, v[132:133]
	global_store_dwordx4 v[54:55], v[50:53], off sc0 sc1 nt
	s_branch .LBB0_1058
; DI unsigned pk2(float a, float b) { f32x2 v = {a, b}; bf16x2_t r = __builtin_convertvector(v, bf16x2_t); return __builtin_bit_cast(unsigned, r); }
; DI float silu_f(float g) { return g * rcpf_(1.f + ex2(-g * LOG2E)); }
; static __device__ __forceinline__ void phase_ffn_up(const P& p, int l, char* lds) {
;     ...
; #pragma unroll
;       for (int jj = 0; jj < 4; ++jj) {
;         const int r = (tid >> 3) + 64 * jj, tt = tstart + r;
;         if (r >= 1 && r <= 254 && tt < MEND) {
;           const int pos = tt < MLAT ? (tt & (TLAT - 1)) : ((tt - MLAT) & (TCTX - 1)), slen = tt < MLAT ? TLAT : TCTX;
;           const float fm = pos == 0 ? 0.f : 1.f, fp = pos == slen - 1 ? 0.f : 1.f;
;           const char* rp = tile + r * 528;
;           float o[8];
; #pragma unroll
;           for (int hf = 0; hf < 2; ++hf) {
;             const f32x4 am = *(const f32x4*)(rp - 528 + lca + hf * 16), a0 = *(const f32x4*)(rp + lca + hf * 16), ap = *(const f32x4*)(rp + 528 + lca + hf * 16);
;             const f32x4 gm = *(const f32x4*)(rp - 528 + lcg + hf * 16), g0 = *(const f32x4*)(rp + lcg + hf * 16), gp = *(const f32x4*)(rp + 528 + lcg + hf * 16);
; #pragma unroll
;             for (int e = 0; e < 4; ++e) {
;               const int q = hf * 4 + e;
;               const float ua = wa0[q] * (fm * am[e]) + wa1[q] * a0[e] + wa2[q] * (fp * ap[e]) + ba[q];
;               const float ug = wg0[q] * (fm * gm[e]) + wg1[q] * g0[e] + wg2[q] * (fp * gp[e]) + bg[q];
;               o[q] = silu_f(ug) * ua;
;             }
;           }
;           u32x4 w = {pk2(o[0], o[1]), pk2(o[2], o[3]), pk2(o[4], o[5]), pk2(o[6], o[7])};
;           *(u32x4*)(act + (size_t)tt * DFF + ca0) = w;
.Lcf_0:
	v_mov_b32_e32 v0, v158
	s_mov_b32 s100, 0xbfb8aa3b
	s_mov_b32 s101, 0xbfb8aa3b
	ds_read_b128 v[160:163], v159 offset:1904
	ds_read_b128 v[164:167], v159 offset:2432
	ds_read_b128 v[168:171], v159 offset:2960
	ds_read_b128 v[172:175], v159 offset:1776
	ds_read_b128 v[176:179], v159 offset:2304
	ds_read_b128 v[136:139], v159 offset:2832
	ds_read_b128 v[182:185], v159 offset:1920
	ds_read_b128 v[186:189], v159 offset:2448
	ds_read_b128 v[190:193], v159 offset:2976
	ds_read_b128 v[194:197], v159 offset:1792
	ds_read_b128 v[200:203], v159 offset:2320
	ds_read_b128 v[204:207], v159 offset:2848
	s_waitcnt lgkmcnt(11)
	v_pk_fma_f32 v[160:161], v[98:99], v[160:161], v[110:111]
	v_pk_fma_f32 v[162:163], v[100:101], v[162:163], v[112:113]
	s_waitcnt lgkmcnt(10)
	v_pk_fma_f32 v[160:161], v[102:103], v[164:165], v[160:161]
	v_pk_fma_f32 v[162:163], v[104:105], v[166:167], v[162:163]
	s_waitcnt lgkmcnt(9)
	v_pk_fma_f32 v[160:161], v[106:107], v[168:169], v[160:161]
	v_pk_fma_f32 v[162:163], v[108:109], v[170:171], v[162:163]
	v_pk_mul_f32 v[164:165], v[160:161], s[100:101]
	v_pk_mul_f32 v[166:167], v[162:163], s[100:101]
	v_exp_f32_e32 v164, v164
	v_exp_f32_e32 v165, v165
	v_exp_f32_e32 v166, v166
	v_exp_f32_e32 v167, v167
	s_waitcnt lgkmcnt(8)
	v_pk_fma_f32 v[172:173], v[86:87], v[172:173], v[82:83]
	v_pk_fma_f32 v[174:175], v[88:89], v[174:175], v[84:85]
	s_waitcnt lgkmcnt(7)
	v_pk_fma_f32 v[172:173], v[94:95], v[176:177], v[172:173]
	v_pk_fma_f32 v[174:175], v[96:97], v[178:179], v[174:175]
	s_waitcnt lgkmcnt(6)
	v_pk_fma_f32 v[172:173], v[90:91], v[136:137], v[172:173]
	v_pk_fma_f32 v[174:175], v[92:93], v[138:139], v[174:175]
	v_add_f32_e32 v164, 1.0, v164
	v_add_f32_e32 v165, 1.0, v165
	v_add_f32_e32 v166, 1.0, v166
	v_add_f32_e32 v167, 1.0, v167
	s_waitcnt lgkmcnt(5)
	v_pk_fma_f32 v[182:183], v[66:67], v[182:183], v[78:79]
	v_pk_fma_f32 v[184:185], v[68:69], v[184:185], v[80:81]
	s_waitcnt lgkmcnt(4)
	v_pk_fma_f32 v[182:183], v[70:71], v[186:187], v[182:183]
	v_pk_fma_f32 v[184:185], v[72:73], v[188:189], v[184:185]
	s_waitcnt lgkmcnt(3)
	v_pk_fma_f32 v[182:183], v[74:75], v[190:191], v[182:183]
	v_pk_fma_f32 v[184:185], v[76:77], v[192:193], v[184:185]
	v_rcp_f32_e32 v164, v164
	v_rcp_f32_e32 v165, v165
	v_rcp_f32_e32 v166, v166
	v_rcp_f32_e32 v167, v167
	v_pk_mul_f32 v[186:187], v[182:183], s[100:101]
	v_pk_mul_f32 v[188:189], v[184:185], s[100:101]
	v_exp_f32_e32 v186, v186
	v_exp_f32_e32 v187, v187
	v_exp_f32_e32 v188, v188
	v_exp_f32_e32 v189, v189
	s_waitcnt lgkmcnt(2)
	v_pk_fma_f32 v[194:195], v[50:51], v[194:195], v[62:63]
	v_pk_fma_f32 v[196:197], v[52:53], v[196:197], v[64:65]
	s_waitcnt lgkmcnt(1)
	v_pk_fma_f32 v[194:195], v[58:59], v[200:201], v[194:195]
	v_pk_fma_f32 v[196:197], v[60:61], v[202:203], v[196:197]
	s_waitcnt lgkmcnt(0)
	v_pk_fma_f32 v[194:195], v[54:55], v[204:205], v[194:195]
	v_pk_fma_f32 v[196:197], v[56:57], v[206:207], v[196:197]
	v_pk_mul_f32 v[160:161], v[160:161], v[164:165]
	v_pk_mul_f32 v[162:163], v[162:163], v[166:167]
	v_pk_mul_f32 v[160:161], v[172:173], v[160:161]
	v_pk_mul_f32 v[162:163], v[174:175], v[162:163]
	v_cvt_pk_bf16_f32 v114, v160, v161
	v_cvt_pk_bf16_f32 v115, v162, v163
	v_add_f32_e32 v186, 1.0, v186
	v_add_f32_e32 v187, 1.0, v187
	v_add_f32_e32 v188, 1.0, v188
	v_add_f32_e32 v189, 1.0, v189
	v_rcp_f32_e32 v186, v186
	v_rcp_f32_e32 v187, v187
	v_rcp_f32_e32 v188, v188
	v_rcp_f32_e32 v189, v189
	s_movk_i32 s14, 0x1600
	v_mad_i64_i32 v[136:137], s[22:23], v0, s14, v[132:133]
	v_pk_mul_f32 v[182:183], v[182:183], v[186:187]
	v_pk_mul_f32 v[184:185], v[184:185], v[188:189]
	v_pk_mul_f32 v[182:183], v[194:195], v[182:183]
	v_pk_mul_f32 v[184:185], v[196:197], v[184:185]
	v_cvt_pk_bf16_f32 v116, v182, v183
	v_cvt_pk_bf16_f32 v117, v184, v185
	global_store_dwordx4 v[136:137], v[114:117], off sc0 sc1 nt
	s_branch .LBB0_1079
.Lcf_1:
	v_mov_b32_e32 v0, v159
	s_mov_b32 s100, 0xbfb8aa3b
	s_mov_b32 s101, 0xbfb8aa3b
	ds_read_b128 v[160:163], v156 offset:1904
	ds_read_b128 v[164:167], v156 offset:2432
	ds_read_b128 v[168:171], v156 offset:2960
	ds_read_b128 v[172:175], v156 offset:1776
	ds_read_b128 v[176:179], v156 offset:2304
	ds_read_b128 v[136:139], v156 offset:2832
	ds_read_b128 v[182:185], v156 offset:1920
	ds_read_b128 v[186:189], v156 offset:2448
	ds_read_b128 v[190:193], v156 offset:2976
	ds_read_b128 v[194:197], v156 offset:1792
	ds_read_b128 v[200:203], v156 offset:2320
	ds_read_b128 v[204:207], v156 offset:2848
	s_waitcnt lgkmcnt(11)
	v_pk_fma_f32 v[160:161], v[98:99], v[160:161], v[110:111]
	v_pk_fma_f32 v[162:163], v[100:101], v[162:163], v[112:113]
	s_waitcnt lgkmcnt(10)
	v_pk_fma_f32 v[160:161], v[102:103], v[164:165], v[160:161]
	v_pk_fma_f32 v[162:163], v[104:105], v[166:167], v[162:163]
	s_waitcnt lgkmcnt(9)
	v_pk_fma_f32 v[160:161], v[106:107], v[168:169], v[160:161]
	v_pk_fma_f32 v[162:163], v[108:109], v[170:171], v[162:163]
	v_pk_mul_f32 v[164:165], v[160:161], s[100:101]
	v_pk_mul_f32 v[166:167], v[162:163], s[100:101]
	v_exp_f32_e32 v164, v164
	v_exp_f32_e32 v165, v165
	v_exp_f32_e32 v166, v166
	v_exp_f32_e32 v167, v167
	s_waitcnt lgkmcnt(8)
	v_pk_fma_f32 v[172:173], v[86:87], v[172:173], v[82:83]
	v_pk_fma_f32 v[174:175], v[88:89], v[174:175], v[84:85]
	s_waitcnt lgkmcnt(7)
	v_pk_fma_f32 v[172:173], v[94:95], v[176:177], v[172:173]
	v_pk_fma_f32 v[174:175], v[96:97], v[178:179], v[174:175]
	s_waitcnt lgkmcnt(6)
	v_pk_fma_f32 v[172:173], v[90:91], v[136:137], v[172:173]
	v_pk_fma_f32 v[174:175], v[92:93], v[138:139], v[174:175]
	v_add_f32_e32 v164, 1.0, v164
	v_add_f32_e32 v165, 1.0, v165
	v_add_f32_e32 v166, 1.0, v166
	v_add_f32_e32 v167, 1.0, v167
	s_waitcnt lgkmcnt(5)
; DI unsigned pk2(float a, float b) { f32x2 v = {a, b}; bf16x2_t r = __builtin_convertvector(v, bf16x2_t); return __builtin_bit_cast(unsigned, r); }
; DI float silu_f(float g) { return g * rcpf_(1.f + ex2(-g * LOG2E)); }
; static __device__ __forceinline__ void phase_ffn_up(const P& p, int l, char* lds) {
;     ...
; #pragma unroll
;       for (int jj = 0; jj < 4; ++jj) {
;         const int r = (tid >> 3) + 64 * jj, tt = tstart + r;
;         if (r >= 1 && r <= 254 && tt < MEND) {
;           const int pos = tt < MLAT ? (tt & (TLAT - 1)) : ((tt - MLAT) & (TCTX - 1)), slen = tt < MLAT ? TLAT : TCTX;
;           const float fm = pos == 0 ? 0.f : 1.f, fp = pos == slen - 1 ? 0.f : 1.f;
;           const char* rp = tile + r * 528;
;           float o[8];
; #pragma unroll
;           for (int hf = 0; hf < 2; ++hf) {
;             const f32x4 am = *(const f32x4*)(rp - 528 + lca + hf * 16), a0 = *(const f32x4*)(rp + lca + hf * 16), ap = *(const f32x4*)(rp + 528 + lca + hf * 16);
;             const f32x4 gm = *(const f32x4*)(rp - 528 + lcg + hf * 16), g0 = *(const f32x4*)(rp + lcg + hf * 16), gp = *(const f32x4*)(rp + 528 + lcg + hf * 16);
; #pragma unroll
;             for (int e = 0; e < 4; ++e) {
;               const int q = hf * 4 + e;
;               const float ua = wa0[q] * (fm * am[e]) + wa1[q] * a0[e] + wa2[q] * (fp * ap[e]) + ba[q];
;               const float ug = wg0[q] * (fm * gm[e]) + wg1[q] * g0[e] + wg2[q] * (fp * gp[e]) + bg[q];
;               o[q] = silu_f(ug) * ua;
;             }
;           }
;           u32x4 w = {pk2(o[0], o[1]), pk2(o[2], o[3]), pk2(o[4], o[5]), pk2(o[6], o[7])};
;           *(u32x4*)(act + (size_t)tt * DFF + ca0) = w;
	v_pk_fma_f32 v[182:183], v[66:67], v[182:183], v[78:79]
	v_pk_fma_f32 v[184:185], v[68:69], v[184:185], v[80:81]
	s_waitcnt lgkmcnt(4)
	v_pk_fma_f32 v[182:183], v[70:71], v[186:187], v[182:183]
	v_pk_fma_f32 v[184:185], v[72:73], v[188:189], v[184:185]
	s_waitcnt lgkmcnt(3)
	v_pk_fma_f32 v[182:183], v[74:75], v[190:191], v[182:183]
	v_pk_fma_f32 v[184:185], v[76:77], v[192:193], v[184:185]
	v_rcp_f32_e32 v164, v164
	v_rcp_f32_e32 v165, v165
	v_rcp_f32_e32 v166, v166
	v_rcp_f32_e32 v167, v167
	v_pk_mul_f32 v[186:187], v[182:183], s[100:101]
	v_pk_mul_f32 v[188:189], v[184:185], s[100:101]
	v_exp_f32_e32 v186, v186
	v_exp_f32_e32 v187, v187
	v_exp_f32_e32 v188, v188
	v_exp_f32_e32 v189, v189
	s_waitcnt lgkmcnt(2)
	v_pk_fma_f32 v[194:195], v[50:51], v[194:195], v[62:63]
	v_pk_fma_f32 v[196:197], v[52:53], v[196:197], v[64:65]
	s_waitcnt lgkmcnt(1)
	v_pk_fma_f32 v[194:195], v[58:59], v[200:201], v[194:195]
	v_pk_fma_f32 v[196:197], v[60:61], v[202:203], v[196:197]
	s_waitcnt lgkmcnt(0)
	v_pk_fma_f32 v[194:195], v[54:55], v[204:205], v[194:195]
	v_pk_fma_f32 v[196:197], v[56:57], v[206:207], v[196:197]
	v_pk_mul_f32 v[160:161], v[160:161], v[164:165]
	v_pk_mul_f32 v[162:163], v[162:163], v[166:167]
	v_pk_mul_f32 v[160:161], v[172:173], v[160:161]
	v_pk_mul_f32 v[162:163], v[174:175], v[162:163]
	v_cvt_pk_bf16_f32 v114, v160, v161
	v_cvt_pk_bf16_f32 v115, v162, v163
	v_add_f32_e32 v186, 1.0, v186
	v_add_f32_e32 v187, 1.0, v187
	v_add_f32_e32 v188, 1.0, v188
	v_add_f32_e32 v189, 1.0, v189
	v_rcp_f32_e32 v186, v186
	v_rcp_f32_e32 v187, v187
	v_rcp_f32_e32 v188, v188
	v_rcp_f32_e32 v189, v189
	s_movk_i32 s14, 0x1600
	v_mad_i64_i32 v[136:137], s[22:23], v0, s14, v[132:133]
	v_pk_mul_f32 v[182:183], v[182:183], v[186:187]
	v_pk_mul_f32 v[184:185], v[184:185], v[188:189]
	v_pk_mul_f32 v[182:183], v[194:195], v[182:183]
	v_pk_mul_f32 v[184:185], v[196:197], v[184:185]
	v_cvt_pk_bf16_f32 v116, v182, v183
	v_cvt_pk_bf16_f32 v117, v184, v185
	global_store_dwordx4 v[136:137], v[114:117], off sc0 sc1 nt
	s_branch .LBB0_1081
.Lcf_2:
	v_mov_b32_e32 v0, v159
	s_mov_b32 s100, 0xbfb8aa3b
	s_mov_b32 s101, 0xbfb8aa3b
	ds_read_b128 v[160:163], v157 offset:1904
	ds_read_b128 v[164:167], v157 offset:2432
	ds_read_b128 v[168:171], v157 offset:2960
	ds_read_b128 v[172:175], v157 offset:1776
	ds_read_b128 v[176:179], v157 offset:2304
	ds_read_b128 v[136:139], v157 offset:2832
	ds_read_b128 v[182:185], v157 offset:1920
	ds_read_b128 v[186:189], v157 offset:2448
	ds_read_b128 v[190:193], v157 offset:2976
	ds_read_b128 v[194:197], v157 offset:1792
	ds_read_b128 v[200:203], v157 offset:2320
	ds_read_b128 v[204:207], v157 offset:2848
	s_waitcnt lgkmcnt(11)
	v_pk_fma_f32 v[160:161], v[98:99], v[160:161], v[110:111]
	v_pk_fma_f32 v[162:163], v[100:101], v[162:163], v[112:113]
	s_waitcnt lgkmcnt(10)
	v_pk_fma_f32 v[160:161], v[102:103], v[164:165], v[160:161]
	v_pk_fma_f32 v[162:163], v[104:105], v[166:167], v[162:163]
	s_waitcnt lgkmcnt(9)
	v_pk_fma_f32 v[160:161], v[106:107], v[168:169], v[160:161]
	v_pk_fma_f32 v[162:163], v[108:109], v[170:171], v[162:163]
	v_pk_mul_f32 v[164:165], v[160:161], s[100:101]
	v_pk_mul_f32 v[166:167], v[162:163], s[100:101]
	v_exp_f32_e32 v164, v164
	v_exp_f32_e32 v165, v165
	v_exp_f32_e32 v166, v166
	v_exp_f32_e32 v167, v167
	s_waitcnt lgkmcnt(8)
	v_pk_fma_f32 v[172:173], v[86:87], v[172:173], v[82:83]
	v_pk_fma_f32 v[174:175], v[88:89], v[174:175], v[84:85]
	s_waitcnt lgkmcnt(7)
	v_pk_fma_f32 v[172:173], v[94:95], v[176:177], v[172:173]
	v_pk_fma_f32 v[174:175], v[96:97], v[178:179], v[174:175]
	s_waitcnt lgkmcnt(6)
	v_pk_fma_f32 v[172:173], v[90:91], v[136:137], v[172:173]
	v_pk_fma_f32 v[174:175], v[92:93], v[138:139], v[174:175]
	v_add_f32_e32 v164, 1.0, v164
	v_add_f32_e32 v165, 1.0, v165
	v_add_f32_e32 v166, 1.0, v166
	v_add_f32_e32 v167, 1.0, v167
	s_waitcnt lgkmcnt(5)
	v_pk_fma_f32 v[182:183], v[66:67], v[182:183], v[78:79]
	v_pk_fma_f32 v[184:185], v[68:69], v[184:185], v[80:81]
	s_waitcnt lgkmcnt(4)
	v_pk_fma_f32 v[182:183], v[70:71], v[186:187], v[182:183]
	v_pk_fma_f32 v[184:185], v[72:73], v[188:189], v[184:185]
	s_waitcnt lgkmcnt(3)
	v_pk_fma_f32 v[182:183], v[74:75], v[190:191], v[182:183]
	v_pk_fma_f32 v[184:185], v[76:77], v[192:193], v[184:185]
	v_rcp_f32_e32 v164, v164
	v_rcp_f32_e32 v165, v165
	v_rcp_f32_e32 v166, v166
	v_rcp_f32_e32 v167, v167
	v_pk_mul_f32 v[186:187], v[182:183], s[100:101]
	v_pk_mul_f32 v[188:189], v[184:185], s[100:101]
	v_exp_f32_e32 v186, v186
	v_exp_f32_e32 v187, v187
	v_exp_f32_e32 v188, v188
	v_exp_f32_e32 v189, v189
	s_waitcnt lgkmcnt(2)
	v_pk_fma_f32 v[194:195], v[50:51], v[194:195], v[62:63]
	v_pk_fma_f32 v[196:197], v[52:53], v[196:197], v[64:65]
	s_waitcnt lgkmcnt(1)
	v_pk_fma_f32 v[194:195], v[58:59], v[200:201], v[194:195]
	v_pk_fma_f32 v[196:197], v[60:61], v[202:203], v[196:197]
	s_waitcnt lgkmcnt(0)
	v_pk_fma_f32 v[194:195], v[54:55], v[204:205], v[194:195]
	v_pk_fma_f32 v[196:197], v[56:57], v[206:207], v[196:197]
	v_pk_mul_f32 v[160:161], v[160:161], v[164:165]
	v_pk_mul_f32 v[162:163], v[162:163], v[166:167]
	v_pk_mul_f32 v[160:161], v[172:173], v[160:161]
	v_pk_mul_f32 v[162:163], v[174:175], v[162:163]
	v_cvt_pk_bf16_f32 v114, v160, v161
	v_cvt_pk_bf16_f32 v115, v162, v163
	v_add_f32_e32 v186, 1.0, v186
	v_add_f32_e32 v187, 1.0, v187
	v_add_f32_e32 v188, 1.0, v188
	v_add_f32_e32 v189, 1.0, v189
	v_rcp_f32_e32 v186, v186
	v_rcp_f32_e32 v187, v187
	v_rcp_f32_e32 v188, v188
	v_rcp_f32_e32 v189, v189
	s_movk_i32 s14, 0x1600
	v_mad_i64_i32 v[136:137], s[22:23], v0, s14, v[132:133]
	v_pk_mul_f32 v[182:183], v[182:183], v[186:187]
	v_pk_mul_f32 v[184:185], v[184:185], v[188:189]
	v_pk_mul_f32 v[182:183], v[194:195], v[182:183]
	v_pk_mul_f32 v[184:185], v[196:197], v[184:185]
	v_cvt_pk_bf16_f32 v116, v182, v183
	v_cvt_pk_bf16_f32 v117, v184, v185
	global_store_dwordx4 v[136:137], v[114:117], off sc0 sc1 nt
	s_branch .LBB0_1083
; DI unsigned pk2(float a, float b) { f32x2 v = {a, b}; bf16x2_t r = __builtin_convertvector(v, bf16x2_t); return __builtin_bit_cast(unsigned, r); }
; DI float silu_f(float g) { return g * rcpf_(1.f + ex2(-g * LOG2E)); }
; static __device__ __forceinline__ void phase_ffn_up(const P& p, int l, char* lds) {
;     ...
; #pragma unroll
;       for (int jj = 0; jj < 4; ++jj) {
;         const int r = (tid >> 3) + 64 * jj, tt = tstart + r;
;         if (r >= 1 && r <= 254 && tt < MEND) {
;           const int pos = tt < MLAT ? (tt & (TLAT - 1)) : ((tt - MLAT) & (TCTX - 1)), slen = tt < MLAT ? TLAT : TCTX;
;           const float fm = pos == 0 ? 0.f : 1.f, fp = pos == slen - 1 ? 0.f : 1.f;
;           const char* rp = tile + r * 528;
;           float o[8];
; #pragma unroll
;           for (int hf = 0; hf < 2; ++hf) {
;             const f32x4 am = *(const f32x4*)(rp - 528 + lca + hf * 16), a0 = *(const f32x4*)(rp + lca + hf * 16), ap = *(const f32x4*)(rp + 528 + lca + hf * 16);
;             const f32x4 gm = *(const f32x4*)(rp - 528 + lcg + hf * 16), g0 = *(const f32x4*)(rp + lcg + hf * 16), gp = *(const f32x4*)(rp + 528 + lcg + hf * 16);
; #pragma unroll
;             for (int e = 0; e < 4; ++e) {
;               const int q = hf * 4 + e;
;               const float ua = wa0[q] * (fm * am[e]) + wa1[q] * a0[e] + wa2[q] * (fp * ap[e]) + ba[q];
;               const float ug = wg0[q] * (fm * gm[e]) + wg1[q] * g0[e] + wg2[q] * (fp * gp[e]) + bg[q];
;               o[q] = silu_f(ug) * ua;
;             }
;           }
;           u32x4 w = {pk2(o[0], o[1]), pk2(o[2], o[3]), pk2(o[4], o[5]), pk2(o[6], o[7])};
;           *(u32x4*)(act + (size_t)tt * DFF + ca0) = w;
.Lcf_3:
	v_mov_b32_e32 v0, v136
	s_mov_b32 s100, 0xbfb8aa3b
	s_mov_b32 s101, 0xbfb8aa3b
	ds_read_b128 v[160:163], v157 offset:35696
	ds_read_b128 v[164:167], v157 offset:36224
	ds_read_b128 v[168:171], v157 offset:36752
	ds_read_b128 v[172:175], v157 offset:35568
	ds_read_b128 v[176:179], v157 offset:36096
	ds_read_b128 v[136:139], v157 offset:36624
	ds_read_b128 v[182:185], v157 offset:35712
	ds_read_b128 v[186:189], v157 offset:36240
	ds_read_b128 v[190:193], v157 offset:36768
	ds_read_b128 v[194:197], v157 offset:35584
	ds_read_b128 v[200:203], v157 offset:36112
	ds_read_b128 v[204:207], v157 offset:36640
	s_waitcnt lgkmcnt(11)
	v_pk_fma_f32 v[160:161], v[98:99], v[160:161], v[110:111]
	v_pk_fma_f32 v[162:163], v[100:101], v[162:163], v[112:113]
	s_waitcnt lgkmcnt(10)
	v_pk_fma_f32 v[160:161], v[102:103], v[164:165], v[160:161]
	v_pk_fma_f32 v[162:163], v[104:105], v[166:167], v[162:163]
	s_waitcnt lgkmcnt(9)
	v_pk_fma_f32 v[160:161], v[106:107], v[168:169], v[160:161]
	v_pk_fma_f32 v[162:163], v[108:109], v[170:171], v[162:163]
	v_pk_mul_f32 v[164:165], v[160:161], s[100:101]
	v_pk_mul_f32 v[166:167], v[162:163], s[100:101]
	v_exp_f32_e32 v164, v164
	v_exp_f32_e32 v165, v165
	v_exp_f32_e32 v166, v166
	v_exp_f32_e32 v167, v167
	s_waitcnt lgkmcnt(8)
	v_pk_fma_f32 v[172:173], v[86:87], v[172:173], v[82:83]
	v_pk_fma_f32 v[174:175], v[88:89], v[174:175], v[84:85]
	s_waitcnt lgkmcnt(7)
	v_pk_fma_f32 v[172:173], v[94:95], v[176:177], v[172:173]
	v_pk_fma_f32 v[174:175], v[96:97], v[178:179], v[174:175]
	s_waitcnt lgkmcnt(6)
	v_pk_fma_f32 v[172:173], v[90:91], v[136:137], v[172:173]
	v_pk_fma_f32 v[174:175], v[92:93], v[138:139], v[174:175]
	v_add_f32_e32 v164, 1.0, v164
	v_add_f32_e32 v165, 1.0, v165
	v_add_f32_e32 v166, 1.0, v166
	v_add_f32_e32 v167, 1.0, v167
	s_waitcnt lgkmcnt(5)
	v_pk_fma_f32 v[182:183], v[66:67], v[182:183], v[78:79]
	v_pk_fma_f32 v[184:185], v[68:69], v[184:185], v[80:81]
	s_waitcnt lgkmcnt(4)
	v_pk_fma_f32 v[182:183], v[70:71], v[186:187], v[182:183]
	v_pk_fma_f32 v[184:185], v[72:73], v[188:189], v[184:185]
	s_waitcnt lgkmcnt(3)
	v_pk_fma_f32 v[182:183], v[74:75], v[190:191], v[182:183]
	v_pk_fma_f32 v[184:185], v[76:77], v[192:193], v[184:185]
	v_rcp_f32_e32 v164, v164
	v_rcp_f32_e32 v165, v165
	v_rcp_f32_e32 v166, v166
	v_rcp_f32_e32 v167, v167
	v_pk_mul_f32 v[186:187], v[182:183], s[100:101]
	v_pk_mul_f32 v[188:189], v[184:185], s[100:101]
	v_exp_f32_e32 v186, v186
	v_exp_f32_e32 v187, v187
	v_exp_f32_e32 v188, v188
	v_exp_f32_e32 v189, v189
	s_waitcnt lgkmcnt(2)
	v_pk_fma_f32 v[194:195], v[50:51], v[194:195], v[62:63]
	v_pk_fma_f32 v[196:197], v[52:53], v[196:197], v[64:65]
	s_waitcnt lgkmcnt(1)
	v_pk_fma_f32 v[194:195], v[58:59], v[200:201], v[194:195]
	v_pk_fma_f32 v[196:197], v[60:61], v[202:203], v[196:197]
	s_waitcnt lgkmcnt(0)
	v_pk_fma_f32 v[194:195], v[54:55], v[204:205], v[194:195]
	v_pk_fma_f32 v[196:197], v[56:57], v[206:207], v[196:197]
	v_pk_mul_f32 v[160:161], v[160:161], v[164:165]
	v_pk_mul_f32 v[162:163], v[162:163], v[166:167]
	v_pk_mul_f32 v[160:161], v[172:173], v[160:161]
	v_pk_mul_f32 v[162:163], v[174:175], v[162:163]
	v_cvt_pk_bf16_f32 v114, v160, v161
	v_cvt_pk_bf16_f32 v115, v162, v163
	v_add_f32_e32 v186, 1.0, v186
	v_add_f32_e32 v187, 1.0, v187
	v_add_f32_e32 v188, 1.0, v188
	v_add_f32_e32 v189, 1.0, v189
	v_rcp_f32_e32 v186, v186
	v_rcp_f32_e32 v187, v187
	v_rcp_f32_e32 v188, v188
	v_rcp_f32_e32 v189, v189
	s_movk_i32 s14, 0x1600
	v_mad_i64_i32 v[136:137], s[22:23], v0, s14, v[132:133]
	v_pk_mul_f32 v[182:183], v[182:183], v[186:187]
	v_pk_mul_f32 v[184:185], v[184:185], v[188:189]
	v_pk_mul_f32 v[182:183], v[194:195], v[182:183]
	v_pk_mul_f32 v[184:185], v[196:197], v[184:185]
	v_cvt_pk_bf16_f32 v116, v182, v183
	v_cvt_pk_bf16_f32 v117, v184, v185
	global_store_dwordx4 v[136:137], v[114:117], off sc0 sc1 nt
	s_branch .LBB0_1058

; DI const float* modv(const P& p, int l, int mi) { return (const float*)(p.ws + OFF_MOD) + ((size_t)l * 9 + mi) * 6144; }
; static __device__ __forceinline__ void phase_resid_gemm(const P& p, int l, const u16* A, const u16* W, int ldk, int gate_off, char* lds, bool from_input = false) {
;     ...
;     float* xb = xrow(p, mt * 256); const float* gv = modv(p, l, modidx(mt * 256)) + gate_off;
; #pragma unroll
;     for (int tn = 0; tn < 2; ++tn) {
;       const int n = nt * 128 + wn * 64 + 32 * tn + r32; const float g = gv[n];
;       float* xp = xb + (size_t)(wm * 64 + 4 * hi) * DM + n;
;       const float* xs = (from_input ? xin(p, mt * 256) : (const float*)xb) + (size_t)(wm * 64 + 4 * hi) * DM + n;
;       float xv[2][16];
; #pragma unroll
;       for (int tm = 0; tm < 2; ++tm)
; #pragma unroll
;         for (int r = 0; r < 16; ++r) xv[tm][r] = __builtin_nontemporal_load(xs + (size_t)(32 * tm + (r & 3) + 8 * (r >> 2)) * DM);
; #pragma unroll
;       for (int tm = 0; tm < 2; ++tm)
; #pragma unroll
;         for (int r = 0; r < 16; ++r) xp[(size_t)(32 * tm + (r & 3) + 8 * (r >> 2)) * DM] = xv[tm][r] + g * acc[tm][tn][r];
.LBB0_1157:
	s_lshl_b32 s20, s17, 8
	s_add_i32 s6, s20, 0xffff0000
	s_ashr_i32 s7, s20, 31
	s_cmpk_lt_i32 s17, 0x100
	s_cselect_b32 s7, s7, 0
	s_cselect_b32 s6, s20, s6
	s_cselect_b32 s9, s63, s65
	s_cselect_b32 s8, s62, s64
	s_lshl_b64 s[6:7], s[6:7], 12
	s_add_u32 s8, s8, s6
	s_addc_u32 s9, s9, s7
	s_min_i32 s6, s20, 0x10000
	s_ashr_i32 s6, s6, 13
	s_ashr_i32 s7, s6, 31
	s_add_u32 s6, s78, s6
	s_addc_u32 s7, s79, s7
	s_mulk_i32 s7, 0x6000
	s_mul_hi_u32 s17, s6, 0x6000
	s_add_i32 s17, s17, s7
	s_mulk_i32 s6, 0x6000
	s_add_u32 s6, s64, s6
	s_addc_u32 s7, s65, s17
	v_lshl_or_b32 v158, s16, 7, v177
	s_add_u32 s6, s6, 0x805000
	v_ashrrev_i32_e32 v159, 31, v158
	s_addc_u32 s7, s7, 0
	v_lshl_add_u64 v[132:133], s[8:9], 0, v[130:131]
	v_lshlrev_b64 v[134:135], 2, v[158:159]
	v_lshl_add_u64 v[136:137], s[6:7], 0, v[134:135]
	v_lshl_add_u64 v[134:135], v[132:133], 0, v[134:135]
	v_add_co_u32_e32 v132, vcc, s80, v134
	global_load_dword v0, v[136:137], off
	s_nop 0
	v_addc_co_u32_e32 v133, vcc, 0, v135, vcc
	v_add_co_u32_e32 v136, vcc, s81, v134
	s_movk_i32 s8, 0x3000
	s_nop 0
	v_addc_co_u32_e32 v137, vcc, 0, v135, vcc
	v_add_co_u32_e32 v138, vcc, s8, v134
	s_mov_b32 s8, 0x8000
	s_nop 0
	v_addc_co_u32_e32 v139, vcc, 0, v135, vcc
	v_add_co_u32_e32 v140, vcc, s8, v134
	s_mov_b32 s8, 0x9000
	s_nop 0
	v_addc_co_u32_e32 v141, vcc, 0, v135, vcc
	v_add_co_u32_e32 v142, vcc, s8, v134
	s_mov_b32 s8, 0xa000
	s_nop 0
	v_addc_co_u32_e32 v143, vcc, 0, v135, vcc
	v_add_co_u32_e32 v144, vcc, s8, v134
	s_mov_b32 s8, 0xb000
	s_nop 0
	v_addc_co_u32_e32 v145, vcc, 0, v135, vcc
	v_add_co_u32_e32 v146, vcc, s8, v134
	s_mov_b32 s8, 0x11000
	s_nop 0
	v_addc_co_u32_e32 v147, vcc, 0, v135, vcc
	v_add_co_u32_e32 v148, vcc, s39, v134
	global_load_dword v159, v[134:135], off nt
	global_load_dword v185, v[138:139], off nt
	v_addc_co_u32_e32 v149, vcc, 0, v135, vcc
	v_add_co_u32_e32 v150, vcc, s8, v134
	s_mov_b32 s8, 0x13000
	s_nop 0
	v_addc_co_u32_e32 v151, vcc, 0, v135, vcc
	v_add_co_u32_e32 v152, vcc, s8, v134
	s_mov_b32 s8, 0x19000
	s_nop 0
	v_addc_co_u32_e32 v153, vcc, 0, v135, vcc
	v_add_co_u32_e32 v154, vcc, s8, v134
	s_mov_b32 s8, 0x1b000
	s_nop 0
	v_addc_co_u32_e32 v155, vcc, 0, v135, vcc
	v_add_co_u32_e32 v156, vcc, s8, v134
	s_mov_b32 s8, 0x21000
	s_nop 0
	v_addc_co_u32_e32 v157, vcc, 0, v135, vcc
	v_add_co_u32_e32 v160, vcc, s8, v134
	s_mov_b32 s8, 0x23000
	s_nop 0
	v_addc_co_u32_e32 v161, vcc, 0, v135, vcc
	v_add_co_u32_e32 v162, vcc, s8, v134
	s_mov_b32 s8, 0x29000
	s_nop 0
	v_addc_co_u32_e32 v163, vcc, 0, v135, vcc
	v_add_co_u32_e32 v164, vcc, s8, v134
	s_mov_b32 s8, 0x2b000
	s_nop 0
	v_addc_co_u32_e32 v165, vcc, 0, v135, vcc
	v_add_co_u32_e32 v166, vcc, s8, v134
	s_mov_b32 s8, 0x31000
	s_nop 0
	v_addc_co_u32_e32 v167, vcc, 0, v135, vcc
	v_add_co_u32_e32 v168, vcc, s8, v134
	global_load_dword v186, v[136:137], off offset:-4096 nt
	global_load_dword v187, v[136:137], off nt
	global_load_dword v188, v[142:143], off offset:-4096 nt
	global_load_dword v189, v[142:143], off nt
	global_load_dword v190, v[146:147], off offset:-4096 nt
	global_load_dword v191, v[146:147], off nt
	v_addc_co_u32_e32 v169, vcc, 0, v135, vcc
	s_mov_b32 s8, 0x33000
	global_load_dword v192, v[150:151], off offset:-4096 nt
	global_load_dword v193, v[150:151], off nt
	global_load_dword v194, v[152:153], off offset:-4096 nt
	global_load_dword v195, v[152:153], off nt
	global_load_dword v196, v[154:155], off offset:-4096 nt
	v_add_co_u32_e32 v170, vcc, s8, v134
	global_load_dword v197, v[154:155], off nt
	global_load_dword v200, v[156:157], off offset:-4096 nt
	global_load_dword v201, v[156:157], off nt
	global_load_dword v202, v[160:161], off offset:-4096 nt
	global_load_dword v203, v[160:161], off nt
	v_addc_co_u32_e32 v171, vcc, 0, v135, vcc
	s_mov_b32 s8, 0x39000
	global_load_dword v204, v[162:163], off offset:-4096 nt
	global_load_dword v205, v[162:163], off nt
	global_load_dword v206, v[164:165], off offset:-4096 nt
	global_load_dword v207, v[164:165], off nt
	global_load_dword v208, v[166:167], off offset:-4096 nt
	global_load_dword v209, v[166:167], off nt
	v_add_co_u32_e32 v172, vcc, s8, v134
	global_load_dword v210, v[168:169], off offset:-4096 nt
	s_nop 0
	v_addc_co_u32_e32 v173, vcc, 0, v135, vcc
	global_load_dword v211, v[168:169], off nt
	global_load_dword v212, v[170:171], off offset:-4096 nt
	global_load_dword v213, v[170:171], off nt
	global_load_dword v214, v[172:173], off offset:-4096 nt
	s_mov_b32 s8, 0x3b000
	v_add_co_u32_e32 v174, vcc, s8, v134
	s_waitcnt vmcnt(28)
	v_fmac_f32_e32 v159, v50, v0
	v_addc_co_u32_e32 v175, vcc, 0, v135, vcc
	global_load_dword v215, v[172:173], off nt
	global_load_dword v216, v[174:175], off offset:-4096 nt
	global_load_dword v217, v[174:175], off nt
	global_load_dword v218, v[134:135], off offset:128 nt
	global_load_dword v219, v[138:139], off offset:128 nt
	global_load_dword v220, v[140:141], off offset:128 nt
	global_load_dword v221, v[144:145], off offset:128 nt
	global_load_dword v222, v[148:149], off offset:128 nt
	global_load_dword v223, v[132:133], off offset:128 nt
	s_waitcnt vmcnt(36)
	v_fmac_f32_e32 v185, v53, v0
	global_store_dword v[134:135], v159, off sc0 sc1 nt
	global_load_dword v159, v[142:143], off offset:128 nt
	s_nop 0
	global_load_dword v226, v[136:137], off offset:128 nt
	s_waitcnt vmcnt(38)
	v_fmac_f32_e32 v186, v51, v0
	s_waitcnt vmcnt(37)
	v_fmac_f32_e32 v187, v52, v0
	s_waitcnt vmcnt(36)
	v_fmac_f32_e32 v188, v54, v0
	s_waitcnt vmcnt(35)
	v_fmac_f32_e32 v189, v55, v0
	s_waitcnt vmcnt(34)
	v_fmac_f32_e32 v190, v56, v0
	s_waitcnt vmcnt(33)
; static __device__ __forceinline__ void phase_resid_gemm(const P& p, int l, const u16* A, const u16* W, int ldk, int gate_off, char* lds, bool from_input = false) {
;     ...
; #pragma unroll
;       for (int tm = 0; tm < 2; ++tm)
; #pragma unroll
;         for (int r = 0; r < 16; ++r) xp[(size_t)(32 * tm + (r & 3) + 8 * (r >> 2)) * DM] = xv[tm][r] + g * acc[tm][tn][r];
	v_fmac_f32_e32 v191, v57, v0
	global_store_dword v[136:137], v186, off offset:-4096 sc0 sc1 nt
	global_store_dword v[136:137], v187, off sc0 sc1 nt
	global_store_dword v[138:139], v185, off sc0 sc1 nt
	global_store_dword v[142:143], v188, off offset:-4096 sc0 sc1 nt
	global_store_dword v[142:143], v189, off sc0 sc1 nt
	global_store_dword v[146:147], v190, off offset:-4096 sc0 sc1 nt
	global_store_dword v[146:147], v191, off sc0 sc1 nt
	s_waitcnt vmcnt(39)
	v_fmac_f32_e32 v192, v58, v0
	s_waitcnt vmcnt(38)
	v_fmac_f32_e32 v193, v59, v0
	s_waitcnt vmcnt(37)
	v_fmac_f32_e32 v194, v60, v0
	s_waitcnt vmcnt(36)
	v_fmac_f32_e32 v195, v61, v0
	s_waitcnt vmcnt(35)
	v_fmac_f32_e32 v196, v62, v0
	global_load_dword v56, v[152:153], off offset:128 nt
	global_load_dword v57, v[150:151], off offset:128 nt
	global_load_dword v185, v[146:147], off offset:128 nt
	s_waitcnt vmcnt(37)
	v_fmac_f32_e32 v197, v63, v0
	global_store_dword v[150:151], v192, off offset:-4096 sc0 sc1 nt
	global_store_dword v[150:151], v193, off sc0 sc1 nt
	global_store_dword v[152:153], v194, off offset:-4096 sc0 sc1 nt
	global_store_dword v[152:153], v195, off sc0 sc1 nt
	global_store_dword v[154:155], v196, off offset:-4096 sc0 sc1 nt
	s_waitcnt vmcnt(41)
	v_fmac_f32_e32 v200, v64, v0
	s_waitcnt vmcnt(40)
	v_fmac_f32_e32 v201, v65, v0
	s_waitcnt vmcnt(39)
	v_fmac_f32_e32 v202, v34, v0
	s_waitcnt vmcnt(38)
	v_fmac_f32_e32 v203, v35, v0
	global_load_dword v58, v[160:161], off offset:128 nt
	global_load_dword v59, v[156:157], off offset:128 nt
	global_load_dword v60, v[154:155], off offset:128 nt
	s_waitcnt vmcnt(40)
	v_fmac_f32_e32 v204, v36, v0
	global_store_dword v[154:155], v197, off sc0 sc1 nt
	global_store_dword v[156:157], v200, off offset:-4096 sc0 sc1 nt
	global_store_dword v[156:157], v201, off sc0 sc1 nt
	global_store_dword v[160:161], v202, off offset:-4096 sc0 sc1 nt
	global_store_dword v[160:161], v203, off sc0 sc1 nt
	s_waitcnt vmcnt(44)
	v_fmac_f32_e32 v205, v37, v0
	s_waitcnt vmcnt(43)
	v_fmac_f32_e32 v206, v38, v0
	s_waitcnt vmcnt(42)
	v_fmac_f32_e32 v207, v39, v0
	s_waitcnt vmcnt(41)
	v_fmac_f32_e32 v208, v40, v0
	s_waitcnt vmcnt(40)
	v_fmac_f32_e32 v209, v41, v0
	global_load_dword v61, v[164:165], off offset:128 nt
	global_load_dword v62, v[162:163], off offset:128 nt
	s_waitcnt vmcnt(41)
	v_fmac_f32_e32 v210, v42, v0
	global_store_dword v[162:163], v204, off offset:-4096 sc0 sc1 nt
	global_store_dword v[162:163], v205, off sc0 sc1 nt
	global_store_dword v[164:165], v206, off offset:-4096 sc0 sc1 nt
	global_store_dword v[164:165], v207, off sc0 sc1 nt
	global_store_dword v[166:167], v208, off offset:-4096 sc0 sc1 nt
	global_store_dword v[166:167], v209, off sc0 sc1 nt
	s_waitcnt vmcnt(46)
	v_fmac_f32_e32 v211, v43, v0
	s_waitcnt vmcnt(45)
	v_fmac_f32_e32 v212, v44, v0
	s_waitcnt vmcnt(44)
	v_fmac_f32_e32 v213, v45, v0
	s_waitcnt vmcnt(43)
	v_fmac_f32_e32 v214, v46, v0
	v_or_b32_e32 v34, 32, v158
	global_load_dword v63, v[170:171], off offset:128 nt
	global_load_dword v64, v[168:169], off offset:128 nt
	global_load_dword v65, v[166:167], off offset:128 nt
	s_waitcnt vmcnt(45)
	v_fmac_f32_e32 v215, v47, v0
	global_store_dword v[168:169], v210, off offset:-4096 sc0 sc1 nt
	global_store_dword v[168:169], v211, off sc0 sc1 nt
	global_store_dword v[170:171], v212, off offset:-4096 sc0 sc1 nt
	global_store_dword v[170:171], v213, off sc0 sc1 nt
	global_store_dword v[172:173], v214, off offset:-4096 sc0 sc1 nt
	s_waitcnt vmcnt(49)
	v_fmac_f32_e32 v216, v48, v0
	s_waitcnt vmcnt(48)
; static __device__ __forceinline__ void phase_resid_gemm(const P& p, int l, const u16* A, const u16* W, int ldk, int gate_off, char* lds, bool from_input = false) {
;     ...
;     for (int tn = 0; tn < 2; ++tn) {
;       const int n = nt * 128 + wn * 64 + 32 * tn + r32; const float g = gv[n];
;       float* xp = xb + (size_t)(wm * 64 + 4 * hi) * DM + n;
;       const float* xs = (from_input ? xin(p, mt * 256) : (const float*)xb) + (size_t)(wm * 64 + 4 * hi) * DM + n;
;       float xv[2][16];
; #pragma unroll
;       for (int tm = 0; tm < 2; ++tm)
; #pragma unroll
;         for (int r = 0; r < 16; ++r) xv[tm][r] = __builtin_nontemporal_load(xs + (size_t)(32 * tm + (r & 3) + 8 * (r >> 2)) * DM);
; #pragma unroll
;       for (int tm = 0; tm < 2; ++tm)
; #pragma unroll
;         for (int r = 0; r < 16; ++r) xp[(size_t)(32 * tm + (r & 3) + 8 * (r >> 2)) * DM] = xv[tm][r] + g * acc[tm][tn][r];
	v_fmac_f32_e32 v217, v49, v0
	v_ashrrev_i32_e32 v35, 31, v34
	global_load_dword v186, v[174:175], off offset:128 nt
	global_load_dword v187, v[172:173], off offset:128 nt
	v_lshl_add_u64 v[34:35], v[34:35], 2, s[6:7]
	global_store_dword v[172:173], v215, off sc0 sc1 nt
	global_store_dword v[174:175], v216, off offset:-4096 sc0 sc1 nt
	global_store_dword v[174:175], v217, off sc0 sc1 nt
	s_mov_b32 s6, 0x12000
	global_load_dword v0, v[34:35], off
	v_add_co_u32_e32 v34, vcc, s6, v134
	s_mov_b32 s6, 0x18000
	s_nop 0
	v_addc_co_u32_e32 v35, vcc, 0, v135, vcc
	v_add_co_u32_e32 v36, vcc, s6, v134
	s_mov_b32 s6, 0x1a000
	s_nop 0
	v_addc_co_u32_e32 v37, vcc, 0, v135, vcc
	v_add_co_u32_e32 v38, vcc, s6, v134
	s_mov_b32 s6, 0x20000
	s_nop 0
	v_addc_co_u32_e32 v39, vcc, 0, v135, vcc
	v_add_co_u32_e32 v40, vcc, s6, v134
	s_mov_b32 s6, 0x22000
	s_nop 0
	v_addc_co_u32_e32 v41, vcc, 0, v135, vcc
	v_add_co_u32_e32 v42, vcc, s6, v134
	s_mov_b32 s6, 0x28000
	s_nop 0
	v_addc_co_u32_e32 v43, vcc, 0, v135, vcc
	v_add_co_u32_e32 v44, vcc, s6, v134
	s_mov_b32 s6, 0x2a000
	s_nop 0
	v_addc_co_u32_e32 v45, vcc, 0, v135, vcc
	v_add_co_u32_e32 v46, vcc, s6, v134
	s_mov_b32 s6, 0x30000
	s_nop 0
	v_addc_co_u32_e32 v47, vcc, 0, v135, vcc
	v_add_co_u32_e32 v48, vcc, s6, v134
	s_mov_b32 s6, 0x32000
	s_nop 0
	v_addc_co_u32_e32 v49, vcc, 0, v135, vcc
	v_add_co_u32_e32 v50, vcc, s6, v134
	s_mov_b32 s6, 0x38000
	s_nop 0
	v_addc_co_u32_e32 v51, vcc, 0, v135, vcc
	v_add_co_u32_e32 v52, vcc, s6, v134
	s_mov_b32 s6, 0x3a000
	s_nop 0
	v_addc_co_u32_e32 v53, vcc, 0, v135, vcc
	v_add_co_u32_e32 v54, vcc, s6, v134
	global_load_dword v158, v[34:35], off offset:128 nt
	global_load_dword v188, v[36:37], off offset:128 nt
	v_addc_co_u32_e32 v55, vcc, 0, v135, vcc
	global_load_dword v189, v[38:39], off offset:128 nt
	global_load_dword v190, v[40:41], off offset:128 nt
	global_load_dword v191, v[42:43], off offset:128 nt
	global_load_dword v192, v[44:45], off offset:128 nt
	global_load_dword v193, v[46:47], off offset:128 nt
	global_load_dword v194, v[48:49], off offset:128 nt
	global_load_dword v195, v[50:51], off offset:128 nt
	global_load_dword v196, v[52:53], off offset:128 nt
	global_load_dword v197, v[54:55], off offset:128 nt
	s_andn2_b64 vcc, exec, s[4:5]
	s_waitcnt vmcnt(11)
	v_fmac_f32_e32 v218, v18, v0
	v_fmac_f32_e32 v223, v19, v0
	v_fmac_f32_e32 v226, v20, v0
	v_fmac_f32_e32 v219, v21, v0
	v_fmac_f32_e32 v220, v22, v0
	v_fmac_f32_e32 v159, v23, v0
	v_fmac_f32_e32 v221, v24, v0
	v_fmac_f32_e32 v185, v25, v0
	v_fmac_f32_e32 v222, v26, v0
	v_fmac_f32_e32 v57, v27, v0
	v_fmac_f32_e32 v56, v29, v0
	v_fmac_f32_e32 v60, v31, v0
	v_fmac_f32_e32 v59, v33, v0
	v_fmac_f32_e32 v58, v3, v0
	v_fmac_f32_e32 v62, v5, v0
	v_fmac_f32_e32 v61, v7, v0
	v_fmac_f32_e32 v65, v9, v0
	v_fmac_f32_e32 v64, v11, v0
	v_fmac_f32_e32 v63, v13, v0
	v_fmac_f32_e32 v187, v15, v0
	v_fmac_f32_e32 v186, v17, v0
	global_store_dword v[134:135], v218, off offset:128 sc0 sc1 nt
	global_store_dword v[132:133], v223, off offset:128 sc0 sc1 nt
	global_store_dword v[136:137], v226, off offset:128 sc0 sc1 nt
	global_store_dword v[138:139], v219, off offset:128 sc0 sc1 nt
	global_store_dword v[140:141], v220, off offset:128 sc0 sc1 nt
	global_store_dword v[142:143], v159, off offset:128 sc0 sc1 nt
	global_store_dword v[144:145], v221, off offset:128 sc0 sc1 nt
	global_store_dword v[146:147], v185, off offset:128 sc0 sc1 nt
	global_store_dword v[148:149], v222, off offset:128 sc0 sc1 nt
	global_store_dword v[150:151], v57, off offset:128 sc0 sc1 nt
	global_store_dword v[152:153], v56, off offset:128 sc0 sc1 nt
	global_store_dword v[154:155], v60, off offset:128 sc0 sc1 nt
	global_store_dword v[156:157], v59, off offset:128 sc0 sc1 nt
	global_store_dword v[160:161], v58, off offset:128 sc0 sc1 nt
	global_store_dword v[162:163], v62, off offset:128 sc0 sc1 nt
	global_store_dword v[164:165], v61, off offset:128 sc0 sc1 nt
	global_store_dword v[166:167], v65, off offset:128 sc0 sc1 nt
	global_store_dword v[168:169], v64, off offset:128 sc0 sc1 nt
	global_store_dword v[170:171], v63, off offset:128 sc0 sc1 nt
	global_store_dword v[172:173], v187, off offset:128 sc0 sc1 nt
	global_store_dword v[174:175], v186, off offset:128 sc0 sc1 nt
	s_waitcnt vmcnt(31)
	v_fmac_f32_e32 v158, v28, v0
	s_waitcnt vmcnt(30)
	v_fmac_f32_e32 v188, v30, v0
	global_store_dword v[34:35], v158, off offset:128 sc0 sc1 nt
	s_waitcnt vmcnt(30)
	v_fmac_f32_e32 v189, v32, v0
	s_waitcnt vmcnt(29)
	v_fmac_f32_e32 v190, v2, v0
	s_waitcnt vmcnt(28)
	v_fmac_f32_e32 v191, v4, v0
	s_waitcnt vmcnt(27)
	v_fmac_f32_e32 v192, v6, v0
	s_waitcnt vmcnt(26)
	v_fmac_f32_e32 v193, v8, v0
	s_waitcnt vmcnt(25)
	v_fmac_f32_e32 v194, v10, v0
	s_waitcnt vmcnt(24)
	v_fmac_f32_e32 v195, v12, v0
	s_waitcnt vmcnt(23)
	v_fmac_f32_e32 v196, v14, v0
	s_waitcnt vmcnt(22)
	v_fmac_f32_e32 v197, v16, v0
	global_store_dword v[36:37], v188, off offset:128 sc0 sc1 nt
	global_store_dword v[38:39], v189, off offset:128 sc0 sc1 nt
	global_store_dword v[40:41], v190, off offset:128 sc0 sc1 nt
	global_store_dword v[42:43], v191, off offset:128 sc0 sc1 nt
	global_store_dword v[44:45], v192, off offset:128 sc0 sc1 nt
	global_store_dword v[46:47], v193, off offset:128 sc0 sc1 nt
	global_store_dword v[48:49], v194, off offset:128 sc0 sc1 nt
	global_store_dword v[50:51], v195, off offset:128 sc0 sc1 nt
	global_store_dword v[52:53], v196, off offset:128 sc0 sc1 nt
	global_store_dword v[54:55], v197, off offset:128 sc0 sc1 nt
	s_cbranch_vccz .LBB0_1176
